# removed cg sync; pipelined sample-conv history loads; hand-pipelined EpiRes epilogues (out-proj, down)
# speedup vs baseline: 1.0457x; 1.0457x over previous
; #define LAS __attribute__((address_space(3)))
; __device__ __forceinline__ unsigned xb_add(unsigned* p, unsigned v) { return __hip_atomic_fetch_add(p, v, __ATOMIC_RELAXED, __HIP_MEMORY_SCOPE_AGENT); }
; __device__ __forceinline__ unsigned xb_xcc_id() { return (unsigned)__builtin_amdgcn_s_getreg((3 << 11) | 20) & 0xFu; }
; __global__ void __launch_bounds__(512, 2) hybrid_fwd(Params P) {
;     extern __shared__ __attribute__((aligned(16))) unsigned char lds[];
;     LAS unsigned char* ldsl = (LAS unsigned char*)lds;
;     const int G0 = gridDim.x, bid0 = blockIdx.x;
;     const int wave0 = __builtin_amdgcn_readfirstlane((int)threadIdx.x >> 6);
;     ...
;     cg::this_grid().sync();
;     ...
;     LAS unsigned long long* ptab = (LAS unsigned long long*)(ldsl + PTAB_OFF);
;     if (threadIdx.x == 0) {
; #pragma unroll
;         for (int i = 0; i < 34; ++i) ptab[i] = (unsigned long long)P.in[i];
;         ptab[34] = (unsigned long long)P.out; ptab[35] = (unsigned long long)P.ws;
;         ((volatile LAS unsigned*)(ldsl + XBST_OFF))[0] = 0u; ((volatile LAS unsigned*)(ldsl + XBST_OFF))[1] = 0u;
;         (void)xb_add((unsigned*)P.ws + XB_XCNT(xb_xcc_id()), 1u); }
;     __syncthreads();
_Z10hybrid_fwd6Params:
	s_add_u32 s4, s0, 0x128
	v_writelane_b32 v253, s2, 0
	s_load_dword s2, s[0:1], 0x128
	v_and_b32_e32 v1, 0x3ff, v0
	v_and_b32_e32 v0, 0x3fffffff, v0
	s_addc_u32 s5, s1, 0
	v_readfirstlane_b32 s26, v1
	s_waitcnt lgkmcnt(0)
	v_writelane_b32 v253, s2, 1
	v_cmp_eq_u32_e32 vcc, 0, v1
	s_and_saveexec_b64 s[2:3], vcc
	s_cbranch_execz .LBB0_13
	s_load_dwordx16 s[8:23], s[0:1], 0x0
	s_add_i32 s4, 0, 0x20400
	v_mov_b32_e32 v4, s4
	s_add_i32 s4, 0, 0x20410
	s_load_dwordx16 s[36:51], s[0:1], 0x80
	s_waitcnt lgkmcnt(0)
	v_mov_b32_e32 v0, s8
	v_mov_b32_e32 v1, s9
	v_mov_b32_e32 v2, s10
	v_mov_b32_e32 v3, s11
	ds_write_b128 v4, v[0:3]
	v_mov_b32_e32 v0, s12
	v_mov_b32_e32 v1, s13
	v_mov_b32_e32 v2, s14
	v_mov_b32_e32 v3, s15
	v_mov_b32_e32 v4, s4
	s_add_i32 s4, 0, 0x20420
	ds_write_b128 v4, v[0:3]
	v_mov_b32_e32 v0, s16
	v_mov_b32_e32 v1, s17
	v_mov_b32_e32 v2, s18
	v_mov_b32_e32 v3, s19
	v_mov_b32_e32 v4, s4
	s_load_dwordx16 s[4:19], s[0:1], 0x40
	ds_write_b128 v4, v[0:3]
	v_mov_b32_e32 v0, s20
	s_add_i32 s20, 0, 0x20430
	v_mov_b32_e32 v1, s21
	v_mov_b32_e32 v2, s22
	v_mov_b32_e32 v3, s23
	v_mov_b32_e32 v4, s20
	ds_write_b128 v4, v[0:3]
	s_waitcnt lgkmcnt(0)
	v_mov_b32_e32 v0, s4
	s_add_i32 s4, 0, 0x20440
	v_mov_b32_e32 v1, s5
	v_mov_b32_e32 v2, s6
	v_mov_b32_e32 v3, s7
	v_mov_b32_e32 v4, s4
	s_add_i32 s4, 0, 0x20450
	ds_write_b128 v4, v[0:3]
	v_mov_b32_e32 v0, s8
	v_mov_b32_e32 v1, s9
	v_mov_b32_e32 v2, s10
	v_mov_b32_e32 v3, s11
	v_mov_b32_e32 v4, s4
	s_add_i32 s4, 0, 0x20460
	ds_write_b128 v4, v[0:3]
	v_mov_b32_e32 v0, s12
	v_mov_b32_e32 v1, s13
	v_mov_b32_e32 v2, s14
	v_mov_b32_e32 v3, s15
	v_mov_b32_e32 v4, s4
	s_add_i32 s4, 0, 0x20470
	ds_write_b128 v4, v[0:3]
	v_mov_b32_e32 v0, s16
	v_mov_b32_e32 v1, s17
	v_mov_b32_e32 v2, s18
	v_mov_b32_e32 v3, s19
	v_mov_b32_e32 v4, s4
	s_add_i32 s4, 0, 0x20480
	ds_write_b128 v4, v[0:3]
	v_mov_b32_e32 v0, s36
	v_mov_b32_e32 v1, s37
	v_mov_b32_e32 v2, s38
	v_mov_b32_e32 v3, s39
	v_mov_b32_e32 v4, s4
	s_add_i32 s4, 0, 0x20490
	ds_write_b128 v4, v[0:3]
	v_mov_b32_e32 v0, s40
	v_mov_b32_e32 v1, s41
	v_mov_b32_e32 v2, s42
	v_mov_b32_e32 v3, s43
	v_mov_b32_e32 v4, s4
	s_add_i32 s4, 0, 0x204a0
	ds_write_b128 v4, v[0:3]
	v_mov_b32_e32 v4, s4
	s_load_dwordx16 s[4:19], s[0:1], 0xc0
	v_mov_b32_e32 v0, s44
	v_mov_b32_e32 v1, s45
	v_mov_b32_e32 v2, s46
	v_mov_b32_e32 v3, s47
	s_add_i32 s20, 0, 0x204b0
	ds_write_b128 v4, v[0:3]
	v_mov_b32_e32 v0, s48
	v_mov_b32_e32 v1, s49
	v_mov_b32_e32 v2, s50
	v_mov_b32_e32 v3, s51
	v_mov_b32_e32 v4, s20
	ds_write_b128 v4, v[0:3]
	s_waitcnt lgkmcnt(0)
	v_mov_b32_e32 v0, s4
	s_add_i32 s4, 0, 0x204c0
	v_mov_b32_e32 v1, s5
	v_mov_b32_e32 v2, s6
	v_mov_b32_e32 v3, s7
	v_mov_b32_e32 v4, s4
	s_add_i32 s4, 0, 0x204d0
	ds_write_b128 v4, v[0:3]
	v_mov_b32_e32 v0, s8
	v_mov_b32_e32 v1, s9
	v_mov_b32_e32 v2, s10
	v_mov_b32_e32 v3, s11
	v_mov_b32_e32 v4, s4
	s_add_i32 s4, 0, 0x204e0
	ds_write_b128 v4, v[0:3]
	v_mov_b32_e32 v4, s4
	s_load_dwordx8 s[4:11], s[0:1], 0x100
	v_mov_b32_e32 v0, s12
	v_mov_b32_e32 v1, s13
	v_mov_b32_e32 v2, s14
	v_mov_b32_e32 v3, s15
	s_add_i32 s12, 0, 0x204f0
	ds_write_b128 v4, v[0:3]
	v_mov_b32_e32 v0, s16
	v_mov_b32_e32 v1, s17
	v_mov_b32_e32 v2, s18
	v_mov_b32_e32 v3, s19
	v_mov_b32_e32 v4, s12
	ds_write_b128 v4, v[0:3]
	s_waitcnt lgkmcnt(0)
	v_mov_b32_e32 v0, s4
	s_add_i32 s4, 0, 0x20500
	v_mov_b32_e32 v1, s5
	v_mov_b32_e32 v2, s6
	v_mov_b32_e32 v3, s7
	v_mov_b32_e32 v4, s4
	s_add_i32 s4, 0, 0x20510
	ds_write_b128 v4, v[0:3]
	v_mov_b32_e32 v0, s8
	v_mov_b32_e32 v1, s9
	v_mov_b32_e32 v2, s10
	v_mov_b32_e32 v3, s11
	v_mov_b32_e32 v4, s4
	s_add_i32 s4, 0, 0x20600
	ds_write_b128 v4, v[0:3]
	v_mov_b32_e32 v0, 0
	v_mov_b32_e32 v1, s4
	s_add_i32 s4, 0, 0x20604
	s_mov_b64 s[24:25], exec
	ds_write_b32 v1, v0
	v_mov_b32_e32 v1, s4
	ds_write_b32 v1, v0
	v_mbcnt_lo_u32_b32 v0, s24, 0
	v_mbcnt_hi_u32_b32 v0, s25, v0
	s_getreg_b32 s4, hwreg(HW_REG_XCC_ID, 0, 4)
	v_cmp_eq_u32_e32 vcc, 0, v0
	s_and_b64 exec, exec, vcc
	s_cbranch_execz .LBB0_13
	s_lshl_b32 s4, s4, 8
	s_and_b32 s4, s4, 0xf00
	s_bcnt1_i32_b64 s5, s[24:25]
	v_mov_b32_e32 v0, s4
	v_mov_b32_e32 v1, s5
	global_atomic_add v0, v1, s[10:11] offset:1024

; __device__ __forceinline__ unsigned cvt_pk_bf16(float lo, float hi) { const f32x2_t v = {lo, hi}; const bf16x2_t b = __builtin_convertvector(v, bf16x2_t); return __builtin_bit_cast(unsigned, b); }
; #define INP(i) ((const float*)ld_ptr(pb, (i)))
; __device__ __forceinline__ void conv_group(const bf16_t* VC, size_t vrow0  , int tvalid0  , const float* hist,
;                                            const float* cw, const float* cb, const float* lg, const float* lb, bf16_t* MIX, size_t orow0, int lane) {
;     const int c4 = lane * 4;
;     u32x2 vr[34];
; #pragma unroll
;     for (int r = 0; r < 34; ++r) {
;         if (hist && r < 30) { const f32x4 h = *(const f32x4*)(hist + (size_t)r * 256 + c4); vr[r] = (u32x2){cvt_pk_bf16(h[0], h[1]), cvt_pk_bf16(h[2], h[3])}; }
;         else if (r < tvalid0) vr[r] = (u32x2){0u, 0u};
;         else vr[r] = *(const u32x2*)(VC + (vrow0 + r - 30) * 256 + c4);
;     }
; __global__ void __launch_bounds__(512, 2) hybrid_fwd(Params P) {
;     ...
;                     } else { const int b = (i - 256) * 8 + wave;
;                         conv_group(VC, (size_t)MP + b * 4, 0, INP(8) + ((size_t)l * NSB + b) * 30 * 256, INP(25) + (size_t)l * 31 * 256, INP(26) + l * 256, INP(27) + l * 256, INP(28) + l * 256, MIX, (size_t)MP + b * 4, lane); }
.LBB0_1164:
	s_cmpk_gt_i32 s18, 0xff
	s_mov_b64 s[0:1], -1
	s_cbranch_scc0 .LBB0_1223
	s_lshl_b32 s0, s18, 3
	s_add_i32 s0, s19, s0
	s_lshl_b32 s1, s0, 2
	ds_read2_b64 v[0:3], v143 offset0:8 offset1:25
	s_ashr_i32 s11, s1, 31
	s_add_u32 s10, s1, 0x4000
	s_addc_u32 s11, s11, 0
	s_ashr_i32 s1, s0, 31
	s_add_u32 s0, s8, s0
	s_addc_u32 s1, s9, s1
	s_waitcnt lgkmcnt(0)
	v_readfirstlane_b32 s13, v1
	v_readfirstlane_b32 s12, v0
	s_mulk_i32 s1, 0x7800
	s_mul_hi_u32 s14, s0, 0x7800
	ds_read2_b64 v[4:7], v143 offset0:26 offset1:27
	ds_read_b64 v[0:1], v143 offset:224
	s_add_i32 s14, s14, s1
	s_mulk_i32 s0, 0x7800
	s_add_u32 s28, s12, s0
	s_addc_u32 s29, s13, s14
	s_cmp_lg_u64 s[12:13], 0
	v_readfirstlane_b32 s24, v3
	v_readfirstlane_b32 s25, v2
	s_waitcnt lgkmcnt(0)
	v_readfirstlane_b32 s26, v5
	v_readfirstlane_b32 s27, v4
	v_readfirstlane_b32 s14, v7
	v_readfirstlane_b32 s17, v6
	v_readfirstlane_b32 s15, v1
	v_readfirstlane_b32 s16, v0
	s_cselect_b64 s[0:1], -1, 0
	s_cmp_eq_u64 s[12:13], 0
	v_lshl_add_u64 v[8:9], v[60:61], 2, s[28:29]
	s_mov_b64 s[12:13], -1
	v_add_co_u32_e32 v18, vcc, 0x4000, v8
	s_nop 1
	v_addc_co_u32_e32 v19, vcc, 0, v9, vcc
	global_load_dwordx4 v[10:13], v[8:9], off
	global_load_dwordx4 v[14:17], v[8:9], off offset:1024
	global_load_dwordx4 v[24:27], v[8:9], off offset:2048
	global_load_dwordx4 v[28:31], v[8:9], off offset:3072
	v_add_co_u32_e32 v8, vcc, 0x1000, v8
	s_nop 1
	v_addc_co_u32_e32 v9, vcc, 0, v9, vcc
	global_load_dwordx4 v[32:35], v[8:9], off
	global_load_dwordx4 v[36:39], v[8:9], off offset:1024
	global_load_dwordx4 v[94:97], v[8:9], off offset:2048
	global_load_dwordx4 v[104:107], v[8:9], off offset:3072
	v_add_co_u32_e32 v8, vcc, 0x1000, v8
	s_nop 1
	v_addc_co_u32_e32 v9, vcc, 0, v9, vcc
	global_load_dwordx4 v[108:111], v[8:9], off
	global_load_dwordx4 v[112:115], v[8:9], off offset:1024
	global_load_dwordx4 v[116:119], v[8:9], off offset:2048
	global_load_dwordx4 v[120:123], v[8:9], off offset:3072
	v_add_co_u32_e32 v8, vcc, 0x1000, v8
	s_nop 1
	v_addc_co_u32_e32 v9, vcc, 0, v9, vcc
	global_load_dwordx4 v[124:127], v[8:9], off
	global_load_dwordx4 v[128:131], v[8:9], off offset:1024
	global_load_dwordx4 v[132:135], v[8:9], off offset:2048
	global_load_dwordx4 v[136:139], v[8:9], off offset:3072
	s_waitcnt vmcnt(15)
	v_cvt_pk_bf16_f32 v2, v10, v11
	v_cvt_pk_bf16_f32 v3, v12, v13
	global_load_dwordx4 v[10:13], v[18:19], off
	s_waitcnt vmcnt(15)
	v_cvt_pk_bf16_f32 v0, v14, v15
	v_cvt_pk_bf16_f32 v1, v16, v17
	global_load_dwordx4 v[14:17], v[18:19], off offset:1024
	s_waitcnt vmcnt(15)
	v_cvt_pk_bf16_f32 v4, v24, v25
	v_cvt_pk_bf16_f32 v5, v26, v27
	global_load_dwordx4 v[24:27], v[18:19], off offset:2048
	s_waitcnt vmcnt(15)
	v_cvt_pk_bf16_f32 v20, v28, v29
	v_cvt_pk_bf16_f32 v21, v30, v31
	global_load_dwordx4 v[28:31], v[18:19], off offset:3072
	v_add_co_u32_e32 v18, vcc, 0x1000, v18
	s_nop 1
	v_addc_co_u32_e32 v19, vcc, 0, v19, vcc
	s_waitcnt vmcnt(15)
	v_cvt_pk_bf16_f32 v6, v32, v33
	v_cvt_pk_bf16_f32 v7, v34, v35
	global_load_dwordx4 v[32:35], v[18:19], off
	s_waitcnt vmcnt(15)
	v_cvt_pk_bf16_f32 v22, v36, v37
	v_cvt_pk_bf16_f32 v23, v38, v39
	global_load_dwordx4 v[36:39], v[18:19], off offset:1024
	s_waitcnt vmcnt(15)
	v_cvt_pk_bf16_f32 v102, v94, v95
	v_cvt_pk_bf16_f32 v103, v96, v97
	global_load_dwordx4 v[94:97], v[18:19], off offset:2048
	s_waitcnt vmcnt(15)
	v_cvt_pk_bf16_f32 v100, v104, v105
	v_cvt_pk_bf16_f32 v101, v106, v107
	global_load_dwordx4 v[104:107], v[18:19], off offset:3072
	v_add_co_u32_e32 v18, vcc, 0x1000, v18
	s_nop 1
	v_addc_co_u32_e32 v19, vcc, 0, v19, vcc
	s_waitcnt vmcnt(15)
	v_cvt_pk_bf16_f32 v58, v108, v109
	v_cvt_pk_bf16_f32 v59, v110, v111
	global_load_dwordx4 v[108:111], v[18:19], off
	s_waitcnt vmcnt(15)
	v_cvt_pk_bf16_f32 v56, v112, v113
	v_cvt_pk_bf16_f32 v57, v114, v115
	global_load_dwordx4 v[112:115], v[18:19], off offset:1024
	s_waitcnt vmcnt(15)
	v_cvt_pk_bf16_f32 v54, v116, v117
	v_cvt_pk_bf16_f32 v55, v118, v119
	global_load_dwordx4 v[116:119], v[18:19], off offset:2048
	s_waitcnt vmcnt(15)
	v_cvt_pk_bf16_f32 v50, v120, v121
	v_cvt_pk_bf16_f32 v51, v122, v123
	global_load_dwordx4 v[120:123], v[18:19], off offset:3072
	v_add_co_u32_e32 v18, vcc, 0x1000, v18
	s_nop 1
	v_addc_co_u32_e32 v19, vcc, 0, v19, vcc
	s_waitcnt vmcnt(15)
	v_cvt_pk_bf16_f32 v52, v124, v125
	v_cvt_pk_bf16_f32 v53, v126, v127
	global_load_dwordx4 v[124:127], v[18:19], off
	s_waitcnt vmcnt(15)
	v_cvt_pk_bf16_f32 v46, v128, v129
	v_cvt_pk_bf16_f32 v47, v130, v131
	global_load_dwordx4 v[128:131], v[18:19], off offset:1024
	s_waitcnt vmcnt(15)
	v_cvt_pk_bf16_f32 v44, v132, v133
	v_cvt_pk_bf16_f32 v45, v134, v135
	s_waitcnt vmcnt(14)
	v_cvt_pk_bf16_f32 v48, v136, v137
	v_cvt_pk_bf16_f32 v49, v138, v139
	s_waitcnt vmcnt(13)
	v_cvt_pk_bf16_f32 v92, v10, v11
	v_cvt_pk_bf16_f32 v93, v12, v13
	s_waitcnt vmcnt(12)
	v_cvt_pk_bf16_f32 v42, v14, v15
	v_cvt_pk_bf16_f32 v43, v16, v17
	s_waitcnt vmcnt(11)
	v_cvt_pk_bf16_f32 v40, v24, v25
	v_cvt_pk_bf16_f32 v41, v26, v27
	s_waitcnt vmcnt(10)
	v_cvt_pk_bf16_f32 v66, v28, v29
	v_cvt_pk_bf16_f32 v67, v30, v31
	s_waitcnt vmcnt(9)
	v_cvt_pk_bf16_f32 v68, v32, v33
	v_cvt_pk_bf16_f32 v69, v34, v35
	s_waitcnt vmcnt(8)
	v_cvt_pk_bf16_f32 v72, v36, v37
	v_cvt_pk_bf16_f32 v73, v38, v39
	s_waitcnt vmcnt(7)
	v_cvt_pk_bf16_f32 v76, v94, v95
	v_cvt_pk_bf16_f32 v77, v96, v97
	s_waitcnt vmcnt(6)
	v_cvt_pk_bf16_f32 v78, v104, v105
	v_cvt_pk_bf16_f32 v79, v106, v107
	s_waitcnt vmcnt(5)
	v_cvt_pk_bf16_f32 v80, v108, v109
	v_cvt_pk_bf16_f32 v81, v110, v111
	s_waitcnt vmcnt(4)
	v_cvt_pk_bf16_f32 v82, v112, v113
	v_cvt_pk_bf16_f32 v83, v114, v115
	s_waitcnt vmcnt(3)
	v_cvt_pk_bf16_f32 v84, v116, v117
	v_cvt_pk_bf16_f32 v85, v118, v119
	s_waitcnt vmcnt(2)
	v_cvt_pk_bf16_f32 v86, v120, v121
	v_cvt_pk_bf16_f32 v87, v122, v123
	s_waitcnt vmcnt(1)
	v_cvt_pk_bf16_f32 v88, v124, v125
	v_cvt_pk_bf16_f32 v89, v126, v127
	s_waitcnt vmcnt(0)
	v_cvt_pk_bf16_f32 v90, v128, v129
	v_cvt_pk_bf16_f32 v91, v130, v131
	s_lshl_b64 s[0:1], s[10:11], 9
	s_branch .LBB0_1286
; __device__ __forceinline__ void conv_group(const bf16_t* VC, size_t vrow0  , int tvalid0  , const float* hist,
;                                            const float* cw, const float* cb, const float* lg, const float* lb, bf16_t* MIX, size_t orow0, int lane) {
;     ...
;     const f32x4 bias = *(const f32x4*)(cb + c4);
;     f32x4 acc[4] = {bias, bias, bias, bias};
; #pragma unroll
;     for (int k = 0; k < 31; ++k) { const f32x4 w = *(const f32x4*)(cw + (size_t)k * 256 + c4);
; #pragma unroll
;         for (int jj = 0; jj < 4; ++jj) { const u32x2 v = vr[k + jj]; acc[jj] += w * (f32x4){bflo(v.x), bfhi(v.x), bflo(v.y), bfhi(v.y)}; } }
.LBB0_1223:
	s_and_b64 vcc, exec, s[0:1]
	s_cbranch_vccz .LBB0_1163
	s_branch .LBB0_1287
.LBB0_1286:
	s_add_u32 s28, s25, s21
	s_addc_u32 s29, s24, s20
	s_lshl_b64 s[12:13], s[74:75], 2
	s_add_u32 s24, s27, s12
	s_addc_u32 s25, s26, s13
	v_lshlrev_b64 v[74:75], 2, v[60:61]
	v_lshl_add_u64 v[8:9], s[24:25], 0, v[74:75]
	global_load_dwordx4 v[8:11], v[8:9], off
	v_lshl_add_u64 v[96:97], s[28:29], 0, v[74:75]
	global_load_dwordx4 v[12:15], v[96:97], off
	global_load_dwordx4 v[16:19], v[96:97], off offset:1024
	global_load_dwordx4 v[36:39], v[96:97], off offset:2048
	global_load_dwordx4 v[32:35], v[96:97], off offset:3072
	v_add_co_u32_e32 v104, vcc, s76, v96
	s_waitcnt vmcnt(0)
	v_lshlrev_b32_e32 v114, 16, v2
	v_addc_co_u32_e32 v105, vcc, 0, v97, vcc
	global_load_dwordx4 v[28:31], v[104:105], off offset:-4096
	v_add_co_u32_e32 v120, vcc, s81, v96
	v_and_b32_e32 v115, 0xffff0000, v2
	s_nop 0
	v_addc_co_u32_e32 v121, vcc, 0, v97, vcc
	global_load_dwordx4 v[24:27], v[120:121], off offset:1024
	v_lshlrev_b32_e32 v116, 16, v3
	v_and_b32_e32 v117, 0xffff0000, v3
	v_lshlrev_b32_e32 v112, 16, v0
	v_and_b32_e32 v113, 0xffff0000, v0
	v_lshlrev_b32_e32 v130, 16, v1
	v_and_b32_e32 v131, 0xffff0000, v1
	global_load_dwordx4 v[0:3], v[120:121], off offset:2048
	v_lshl_add_u64 v[64:65], v[62:63], 0, s[0:1]
	v_lshlrev_b32_e32 v126, 16, v4
	v_and_b32_e32 v127, 0xffff0000, v4
	v_lshlrev_b32_e32 v128, 16, v5
	v_and_b32_e32 v129, 0xffff0000, v5
	v_lshlrev_b32_e32 v122, 16, v20
	v_and_b32_e32 v123, 0xffff0000, v20
	v_lshlrev_b32_e32 v124, 16, v21
	v_and_b32_e32 v125, 0xffff0000, v21
	v_lshlrev_b32_e32 v110, 16, v6
	v_and_b32_e32 v111, 0xffff0000, v6
	v_lshlrev_b32_e32 v118, 16, v7
	v_and_b32_e32 v119, 0xffff0000, v7
	v_lshlrev_b32_e32 v106, 16, v22
	v_and_b32_e32 v107, 0xffff0000, v22
	v_lshlrev_b32_e32 v108, 16, v23
	v_and_b32_e32 v109, 0xffff0000, v23
	global_load_dwordx2 v[98:99], v[64:65], off
	global_load_dwordx2 v[94:95], v[64:65], off offset:512
	global_load_dwordx2 v[70:71], v[64:65], off offset:1024
	s_nop 0
	global_load_dwordx2 v[64:65], v[64:65], off offset:1536
	s_nop 0
	global_load_dwordx4 v[20:23], v[120:121], off offset:3072
	global_load_dwordx4 v[4:7], v[104:105], off
	s_add_u32 s0, s17, s12
	s_addc_u32 s1, s14, s13
	s_add_u32 s12, s16, s12
	s_addc_u32 s13, s15, s13
	s_movk_i32 s24, 0x7e
	v_pk_fma_f32 v[114:115], v[12:13], v[114:115], v[8:9]
	v_pk_fma_f32 v[120:121], v[14:15], v[130:131], v[10:11]
	v_pk_fma_f32 v[132:133], v[12:13], v[112:113], v[8:9]
	v_pk_fma_f32 v[116:117], v[14:15], v[116:117], v[10:11]
	v_pk_fma_f32 v[134:135], v[14:15], v[128:129], v[10:11]
	v_pk_fma_f32 v[136:137], v[12:13], v[126:127], v[8:9]
	v_pk_fma_f32 v[10:11], v[14:15], v[124:125], v[10:11]
	v_pk_fma_f32 v[8:9], v[12:13], v[122:123], v[8:9]
	v_pk_fma_f32 v[12:13], v[16:17], v[112:113], v[114:115]
	v_pk_fma_f32 v[112:113], v[16:17], v[126:127], v[132:133]
	v_pk_fma_f32 v[114:115], v[18:19], v[128:129], v[120:121]
	v_pk_fma_f32 v[14:15], v[18:19], v[130:131], v[116:117]
	v_pk_fma_f32 v[116:117], v[16:17], v[122:123], v[136:137]
	v_pk_fma_f32 v[120:121], v[18:19], v[124:125], v[134:135]
	v_pk_fma_f32 v[8:9], v[16:17], v[110:111], v[8:9]
	v_pk_fma_f32 v[10:11], v[18:19], v[118:119], v[10:11]
	v_pk_fma_f32 v[16:17], v[38:39], v[124:125], v[114:115]
	v_pk_fma_f32 v[18:19], v[36:37], v[122:123], v[112:113]
	v_pk_fma_f32 v[14:15], v[38:39], v[128:129], v[14:15]
	v_pk_fma_f32 v[12:13], v[36:37], v[126:127], v[12:13]
	v_pk_fma_f32 v[112:113], v[38:39], v[118:119], v[120:121]
	v_pk_fma_f32 v[114:115], v[36:37], v[110:111], v[116:117]
	v_pk_fma_f32 v[10:11], v[38:39], v[108:109], v[10:11]
	v_pk_fma_f32 v[38:39], v[32:33], v[110:111], v[18:19]
	v_pk_fma_f32 v[116:117], v[34:35], v[118:119], v[16:17]
	global_load_dwordx4 v[16:19], v[104:105], off offset:1024
	v_pk_fma_f32 v[36:37], v[36:37], v[106:107], v[8:9]
	v_pk_fma_f32 v[12:13], v[32:33], v[122:123], v[12:13]
	v_pk_fma_f32 v[14:15], v[34:35], v[124:125], v[14:15]
	v_lshlrev_b32_e32 v8, 16, v102
	v_and_b32_e32 v9, 0xffff0000, v102
	v_lshlrev_b32_e32 v102, 16, v103
	v_and_b32_e32 v103, 0xffff0000, v103
	v_pk_fma_f32 v[114:115], v[32:33], v[106:107], v[114:115]
	v_pk_fma_f32 v[112:113], v[34:35], v[108:109], v[112:113]
	v_pk_fma_f32 v[32:33], v[32:33], v[8:9], v[36:37]
	v_pk_fma_f32 v[10:11], v[34:35], v[102:103], v[10:11]
	s_waitcnt vmcnt(9)
	v_pk_fma_f32 v[34:35], v[30:31], v[118:119], v[14:15]
	v_pk_fma_f32 v[36:37], v[28:29], v[110:111], v[12:13]
	global_load_dwordx4 v[12:15], v[104:105], off offset:2048
	v_pk_fma_f32 v[110:111], v[30:31], v[108:109], v[116:117]
	v_pk_fma_f32 v[116:117], v[28:29], v[106:107], v[38:39]
	v_lshlrev_b32_e32 v38, 16, v100
	v_and_b32_e32 v39, 0xffff0000, v100
	v_lshlrev_b32_e32 v100, 16, v101
	v_and_b32_e32 v101, 0xffff0000, v101
	s_waitcnt vmcnt(9)
	v_pk_fma_f32 v[106:107], v[24:25], v[106:107], v[36:37]
	v_add_co_u32_e32 v36, vcc, s77, v96
	v_pk_fma_f32 v[112:113], v[30:31], v[102:103], v[112:113]
	v_pk_fma_f32 v[114:115], v[28:29], v[8:9], v[114:115]
	v_pk_fma_f32 v[10:11], v[30:31], v[100:101], v[10:11]
	v_pk_fma_f32 v[28:29], v[28:29], v[38:39], v[32:33]
	v_pk_fma_f32 v[30:31], v[26:27], v[108:109], v[34:35]
	global_load_dwordx4 v[32:35], v[104:105], off offset:3072
	v_lshlrev_b32_e32 v104, 16, v58
	v_and_b32_e32 v105, 0xffff0000, v58
	v_lshlrev_b32_e32 v58, 16, v59
	v_and_b32_e32 v59, 0xffff0000, v59
	v_addc_co_u32_e32 v37, vcc, 0, v97, vcc
	v_pk_fma_f32 v[108:109], v[26:27], v[102:103], v[110:111]
	v_pk_fma_f32 v[110:111], v[24:25], v[8:9], v[116:117]
	v_pk_fma_f32 v[112:113], v[26:27], v[100:101], v[112:113]
	v_pk_fma_f32 v[114:115], v[24:25], v[38:39], v[114:115]
	v_pk_fma_f32 v[116:117], v[26:27], v[58:59], v[10:11]
	v_pk_fma_f32 v[118:119], v[24:25], v[104:105], v[28:29]
	global_load_dwordx4 v[24:27], v[36:37], off offset:-4096
	v_add_co_u32_e32 v28, vcc, s89, v96
	s_waitcnt vmcnt(10)
; __device__ __forceinline__ void conv_group(const bf16_t* VC, size_t vrow0  , int tvalid0  , const float* hist,
;                                            const float* cw, const float* cb, const float* lg, const float* lb, bf16_t* MIX, size_t orow0, int lane) {
;     ...
;     for (int k = 0; k < 31; ++k) { const f32x4 w = *(const f32x4*)(cw + (size_t)k * 256 + c4);
; #pragma unroll
;         for (int jj = 0; jj < 4; ++jj) { const u32x2 v = vr[k + jj]; acc[jj] += w * (f32x4){bflo(v.x), bfhi(v.x), bflo(v.y), bfhi(v.y)}; } }
	v_pk_fma_f32 v[30:31], v[2:3], v[102:103], v[30:31]
	v_addc_co_u32_e32 v29, vcc, 0, v97, vcc
	v_pk_fma_f32 v[102:103], v[0:1], v[8:9], v[106:107]
	global_load_dwordx4 v[8:11], v[28:29], off offset:1024
	v_pk_fma_f32 v[106:107], v[2:3], v[100:101], v[108:109]
	v_pk_fma_f32 v[108:109], v[0:1], v[38:39], v[110:111]
	v_pk_fma_f32 v[110:111], v[2:3], v[58:59], v[112:113]
	v_pk_fma_f32 v[112:113], v[0:1], v[104:105], v[114:115]
	v_lshlrev_b32_e32 v114, 16, v56
	v_and_b32_e32 v115, 0xffff0000, v56
	v_lshlrev_b32_e32 v56, 16, v57
	v_and_b32_e32 v57, 0xffff0000, v57
	v_pk_fma_f32 v[2:3], v[2:3], v[56:57], v[116:117]
	v_pk_fma_f32 v[0:1], v[0:1], v[114:115], v[118:119]
	s_waitcnt vmcnt(6)
	v_pk_fma_f32 v[30:31], v[22:23], v[100:101], v[30:31]
	v_pk_fma_f32 v[100:101], v[22:23], v[58:59], v[106:107]
	v_pk_fma_f32 v[106:107], v[22:23], v[56:57], v[110:111]
	v_lshlrev_b32_e32 v110, 16, v54
	v_and_b32_e32 v111, 0xffff0000, v54
	v_lshlrev_b32_e32 v54, 16, v55
	v_and_b32_e32 v55, 0xffff0000, v55
	v_pk_fma_f32 v[38:39], v[20:21], v[38:39], v[102:103]
	v_pk_fma_f32 v[102:103], v[20:21], v[104:105], v[108:109]
	v_pk_fma_f32 v[108:109], v[20:21], v[114:115], v[112:113]
	v_pk_fma_f32 v[112:113], v[22:23], v[54:55], v[2:3]
	v_pk_fma_f32 v[116:117], v[20:21], v[110:111], v[0:1]
	global_load_dwordx4 v[20:23], v[28:29], off offset:2048
	s_waitcnt vmcnt(6)
	v_pk_fma_f32 v[30:31], v[6:7], v[58:59], v[30:31]
	v_pk_fma_f32 v[58:59], v[6:7], v[56:57], v[100:101]
	v_pk_fma_f32 v[100:101], v[4:5], v[114:115], v[102:103]
	v_lshlrev_b32_e32 v0, 16, v50
	v_and_b32_e32 v1, 0xffff0000, v50
	v_lshlrev_b32_e32 v2, 16, v51
	v_and_b32_e32 v3, 0xffff0000, v51
	s_waitcnt vmcnt(5)
	v_pk_fma_f32 v[50:51], v[18:19], v[56:57], v[30:31]
	global_load_dwordx4 v[28:31], v[28:29], off offset:3072
	v_pk_fma_f32 v[56:57], v[18:19], v[54:55], v[58:59]
	v_pk_fma_f32 v[58:59], v[16:17], v[110:111], v[100:101]
	v_pk_fma_f32 v[102:103], v[6:7], v[54:55], v[106:107]
	v_pk_fma_f32 v[38:39], v[4:5], v[104:105], v[38:39]
	v_pk_fma_f32 v[104:105], v[4:5], v[110:111], v[108:109]
	v_pk_fma_f32 v[6:7], v[6:7], v[2:3], v[112:113]
	v_pk_fma_f32 v[4:5], v[4:5], v[0:1], v[116:117]
	v_pk_fma_f32 v[38:39], v[16:17], v[114:115], v[38:39]
	v_pk_fma_f32 v[100:101], v[18:19], v[2:3], v[102:103]
	v_pk_fma_f32 v[102:103], v[16:17], v[0:1], v[104:105]
	v_lshlrev_b32_e32 v104, 16, v52
	v_and_b32_e32 v105, 0xffff0000, v52
	s_waitcnt vmcnt(5)
	v_pk_fma_f32 v[50:51], v[14:15], v[54:55], v[50:51]
	v_pk_fma_f32 v[54:55], v[14:15], v[2:3], v[56:57]
	v_pk_fma_f32 v[106:107], v[12:13], v[0:1], v[58:59]
	global_load_dwordx4 v[56:59], v[36:37], off
	v_lshlrev_b32_e32 v52, 16, v53
	v_and_b32_e32 v53, 0xffff0000, v53
	v_pk_fma_f32 v[18:19], v[18:19], v[52:53], v[6:7]
	v_pk_fma_f32 v[16:17], v[16:17], v[104:105], v[4:5]
	v_pk_fma_f32 v[38:39], v[12:13], v[110:111], v[38:39]
	v_lshlrev_b32_e32 v4, 16, v46
	v_and_b32_e32 v5, 0xffff0000, v46
	v_lshlrev_b32_e32 v6, 16, v47
	v_and_b32_e32 v7, 0xffff0000, v47
	v_pk_fma_f32 v[100:101], v[14:15], v[52:53], v[100:101]
	v_pk_fma_f32 v[102:103], v[12:13], v[104:105], v[102:103]
	v_pk_fma_f32 v[18:19], v[14:15], v[6:7], v[18:19]
	v_pk_fma_f32 v[16:17], v[12:13], v[4:5], v[16:17]
	s_waitcnt vmcnt(5)
	v_pk_fma_f32 v[0:1], v[32:33], v[0:1], v[38:39]
	v_pk_fma_f32 v[38:39], v[34:35], v[52:53], v[54:55]
	v_lshlrev_b32_e32 v12, 16, v44
	v_and_b32_e32 v13, 0xffff0000, v44
	v_lshlrev_b32_e32 v14, 16, v45
	v_and_b32_e32 v15, 0xffff0000, v45
	v_pk_fma_f32 v[2:3], v[34:35], v[2:3], v[50:51]
	v_pk_fma_f32 v[46:47], v[32:33], v[104:105], v[106:107]
	v_pk_fma_f32 v[50:51], v[34:35], v[6:7], v[100:101]
	v_pk_fma_f32 v[54:55], v[32:33], v[4:5], v[102:103]
	v_pk_fma_f32 v[18:19], v[34:35], v[14:15], v[18:19]
	v_pk_fma_f32 v[34:35], v[32:33], v[12:13], v[16:17]
	s_waitcnt vmcnt(4)
	v_pk_fma_f32 v[100:101], v[26:27], v[6:7], v[38:39]
	v_lshlrev_b32_e32 v32, 16, v48
	v_and_b32_e32 v33, 0xffff0000, v48
	v_lshlrev_b32_e32 v38, 16, v49
	v_and_b32_e32 v39, 0xffff0000, v49
	v_pk_fma_f32 v[102:103], v[24:25], v[4:5], v[46:47]
	global_load_dwordx4 v[44:47], v[36:37], off offset:1024
	v_pk_fma_f32 v[16:17], v[26:27], v[38:39], v[18:19]
	v_pk_fma_f32 v[18:19], v[24:25], v[32:33], v[34:35]
	v_add_co_u32_e32 v34, vcc, s80, v96
	v_pk_fma_f32 v[2:3], v[26:27], v[52:53], v[2:3]
	v_pk_fma_f32 v[52:53], v[24:25], v[104:105], v[0:1]
	v_pk_fma_f32 v[106:107], v[26:27], v[14:15], v[50:51]
	global_load_dwordx4 v[48:51], v[36:37], off offset:2048
	v_addc_co_u32_e32 v35, vcc, 0, v97, vcc
	v_pk_fma_f32 v[0:1], v[24:25], v[12:13], v[54:55]
	s_waitcnt vmcnt(5)
	v_pk_fma_f32 v[26:27], v[8:9], v[4:5], v[52:53]
	global_load_dwordx4 v[52:55], v[36:37], off offset:3072
	v_add_co_u32_e32 v110, vcc, s93, v96
	v_pk_fma_f32 v[24:25], v[10:11], v[6:7], v[2:3]
	v_pk_fma_f32 v[108:109], v[8:9], v[32:33], v[0:1]
	global_load_dwordx4 v[0:3], v[34:35], off offset:-4096
	v_addc_co_u32_e32 v111, vcc, 0, v97, vcc
	v_pk_fma_f32 v[104:105], v[8:9], v[12:13], v[102:103]
	global_load_dwordx4 v[4:7], v[110:111], off offset:1024
	v_lshlrev_b32_e32 v36, 16, v92
	v_and_b32_e32 v37, 0xffff0000, v92
	v_lshlrev_b32_e32 v102, 16, v93
	v_and_b32_e32 v103, 0xffff0000, v93
	v_pk_fma_f32 v[100:101], v[10:11], v[14:15], v[100:101]
	v_pk_fma_f32 v[106:107], v[10:11], v[38:39], v[106:107]
	v_pk_fma_f32 v[112:113], v[10:11], v[102:103], v[16:17]
	v_pk_fma_f32 v[114:115], v[8:9], v[36:37], v[18:19]
	global_load_dwordx4 v[8:11], v[110:111], off offset:2048
	s_waitcnt vmcnt(8)
; __device__ __forceinline__ void conv_group(const bf16_t* VC, size_t vrow0  , int tvalid0  , const float* hist,
;                                            const float* cw, const float* cb, const float* lg, const float* lb, bf16_t* MIX, size_t orow0, int lane) {
;     ...
;     for (int k = 0; k < 31; ++k) { const f32x4 w = *(const f32x4*)(cw + (size_t)k * 256 + c4);
; #pragma unroll
;         for (int jj = 0; jj < 4; ++jj) { const u32x2 v = vr[k + jj]; acc[jj] += w * (f32x4){bflo(v.x), bfhi(v.x), bflo(v.y), bfhi(v.y)}; } }
;     const f32x4 gg = *(const f32x4*)(lg + c4), bb = *(const f32x4*)(lb + c4);
	v_pk_fma_f32 v[24:25], v[22:23], v[14:15], v[24:25]
	v_pk_fma_f32 v[26:27], v[20:21], v[12:13], v[26:27]
	global_load_dwordx4 v[12:15], v[110:111], off offset:3072
	v_pk_fma_f32 v[116:117], v[22:23], v[38:39], v[100:101]
	v_lshlrev_b32_e32 v92, 16, v42
	v_and_b32_e32 v93, 0xffff0000, v42
	v_lshlrev_b32_e32 v100, 16, v43
	v_and_b32_e32 v101, 0xffff0000, v43
	global_load_dwordx4 v[16:19], v[34:35], off
	v_pk_fma_f32 v[104:105], v[20:21], v[32:33], v[104:105]
	v_pk_fma_f32 v[106:107], v[22:23], v[102:103], v[106:107]
	v_pk_fma_f32 v[108:109], v[20:21], v[36:37], v[108:109]
	v_pk_fma_f32 v[110:111], v[22:23], v[100:101], v[112:113]
	v_pk_fma_f32 v[114:115], v[20:21], v[92:93], v[114:115]
	global_load_dwordx4 v[20:23], v[34:35], off offset:1024
	s_waitcnt vmcnt(10)
	v_pk_fma_f32 v[118:119], v[30:31], v[38:39], v[24:25]
	v_pk_fma_f32 v[32:33], v[28:29], v[32:33], v[26:27]
	v_pk_fma_f32 v[42:43], v[28:29], v[36:37], v[104:105]
	v_pk_fma_f32 v[104:105], v[30:31], v[100:101], v[106:107]
	v_pk_fma_f32 v[106:107], v[28:29], v[92:93], v[108:109]
	v_lshlrev_b32_e32 v112, 16, v40
	v_and_b32_e32 v113, 0xffff0000, v40
	global_load_dwordx4 v[24:27], v[34:35], off offset:2048
	v_lshlrev_b32_e32 v108, 16, v41
	v_and_b32_e32 v109, 0xffff0000, v41
	v_add_co_u32_e32 v40, vcc, s94, v96
	v_pk_fma_f32 v[38:39], v[30:31], v[102:103], v[116:117]
	v_pk_fma_f32 v[110:111], v[30:31], v[108:109], v[110:111]
	v_pk_fma_f32 v[114:115], v[28:29], v[112:113], v[114:115]
	global_load_dwordx4 v[28:31], v[34:35], off offset:3072
	v_addc_co_u32_e32 v41, vcc, 0, v97, vcc
	s_waitcnt vmcnt(11)
	v_pk_fma_f32 v[116:117], v[56:57], v[36:37], v[32:33]
	global_load_dwordx4 v[32:35], v[40:41], off
	v_pk_fma_f32 v[96:97], v[58:59], v[100:101], v[38:39]
	global_load_dwordx4 v[36:39], v[40:41], off offset:1024
	v_pk_fma_f32 v[102:103], v[58:59], v[102:103], v[118:119]
	v_pk_fma_f32 v[118:119], v[56:57], v[92:93], v[42:43]
	global_load_dwordx4 v[40:43], v[40:41], off offset:2048
	v_lshlrev_b32_e32 v124, 16, v66
	v_and_b32_e32 v125, 0xffff0000, v66
	v_lshlrev_b32_e32 v126, 16, v67
	v_and_b32_e32 v127, 0xffff0000, v67
	v_pk_fma_f32 v[132:133], v[58:59], v[108:109], v[104:105]
	v_pk_fma_f32 v[134:135], v[56:57], v[112:113], v[106:107]
	v_pk_fma_f32 v[136:137], v[58:59], v[126:127], v[110:111]
	v_pk_fma_f32 v[128:129], v[56:57], v[124:125], v[114:115]
	s_waitcnt vmcnt(13)
	v_pk_fma_f32 v[56:57], v[46:47], v[100:101], v[102:103]
	v_pk_fma_f32 v[58:59], v[44:45], v[92:93], v[116:117]
	v_lshlrev_b32_e32 v120, 16, v68
	v_and_b32_e32 v121, 0xffff0000, v68
	v_lshlrev_b32_e32 v122, 16, v69
	v_and_b32_e32 v123, 0xffff0000, v69
	v_lshlrev_b32_e32 v114, 16, v72
	v_and_b32_e32 v115, 0xffff0000, v72
	s_waitcnt vmcnt(12)
	v_pk_fma_f32 v[56:57], v[50:51], v[108:109], v[56:57]
	v_pk_fma_f32 v[58:59], v[48:49], v[112:113], v[58:59]
	v_lshlrev_b32_e32 v116, 16, v73
	v_and_b32_e32 v117, 0xffff0000, v73
	v_pk_fma_f32 v[130:131], v[46:47], v[108:109], v[96:97]
	s_waitcnt vmcnt(11)
	v_pk_fma_f32 v[56:57], v[54:55], v[126:127], v[56:57]
	v_pk_fma_f32 v[58:59], v[52:53], v[124:125], v[58:59]
	v_lshlrev_b32_e32 v108, 16, v76
	v_and_b32_e32 v109, 0xffff0000, v76
	v_lshlrev_b32_e32 v110, 16, v77
	s_waitcnt vmcnt(10)
	v_pk_fma_f32 v[56:57], v[2:3], v[122:123], v[56:57]
	v_pk_fma_f32 v[58:59], v[0:1], v[120:121], v[58:59]
	v_and_b32_e32 v111, 0xffff0000, v77
	v_lshlrev_b32_e32 v100, 16, v78
	s_waitcnt vmcnt(9)
	v_pk_fma_f32 v[56:57], v[6:7], v[116:117], v[56:57]
	v_pk_fma_f32 v[58:59], v[4:5], v[114:115], v[58:59]
	v_and_b32_e32 v101, 0xffff0000, v78
	v_lshlrev_b32_e32 v102, 16, v79
	v_and_b32_e32 v103, 0xffff0000, v79
	v_lshlrev_b32_e32 v104, 16, v80
	v_and_b32_e32 v105, 0xffff0000, v80
	v_lshlrev_b32_e32 v106, 16, v81
	v_and_b32_e32 v107, 0xffff0000, v81
	s_waitcnt vmcnt(8)
	v_pk_fma_f32 v[56:57], v[10:11], v[110:111], v[56:57]
	v_pk_fma_f32 v[58:59], v[8:9], v[108:109], v[58:59]
	v_lshlrev_b32_e32 v80, 16, v82
	s_waitcnt vmcnt(7)
	v_pk_fma_f32 v[56:57], v[14:15], v[102:103], v[56:57]
	v_pk_fma_f32 v[58:59], v[12:13], v[100:101], v[58:59]
	v_and_b32_e32 v81, 0xffff0000, v82
	v_lshlrev_b32_e32 v92, 16, v83
	v_and_b32_e32 v93, 0xffff0000, v83
	v_lshlrev_b32_e32 v96, 16, v84
	s_waitcnt vmcnt(6)
	v_pk_fma_f32 v[56:57], v[18:19], v[106:107], v[56:57]
	v_pk_fma_f32 v[58:59], v[16:17], v[104:105], v[58:59]
	v_and_b32_e32 v97, 0xffff0000, v84
	v_lshlrev_b32_e32 v84, 16, v85
	v_and_b32_e32 v85, 0xffff0000, v85
	v_lshlrev_b32_e32 v68, 16, v86
	s_waitcnt vmcnt(5)
	v_pk_fma_f32 v[56:57], v[22:23], v[92:93], v[56:57]
	v_pk_fma_f32 v[58:59], v[20:21], v[80:81], v[58:59]
	v_and_b32_e32 v69, 0xffff0000, v86
	v_lshlrev_b32_e32 v76, 16, v87
	v_and_b32_e32 v77, 0xffff0000, v87
	v_lshlrev_b32_e32 v78, 16, v88
	v_and_b32_e32 v79, 0xffff0000, v88
	v_lshlrev_b32_e32 v82, 16, v89
	s_waitcnt vmcnt(4)
	v_pk_fma_f32 v[66:67], v[26:27], v[84:85], v[56:57]
	v_pk_fma_f32 v[72:73], v[24:25], v[96:97], v[58:59]
	v_and_b32_e32 v83, 0xffff0000, v89
	v_lshlrev_b32_e32 v56, 16, v90
	v_and_b32_e32 v57, 0xffff0000, v90
	v_lshlrev_b32_e32 v58, 16, v91
	v_and_b32_e32 v59, 0xffff0000, v91
	s_waitcnt vmcnt(3)
	v_pk_fma_f32 v[86:87], v[30:31], v[76:77], v[66:67]
	v_pk_fma_f32 v[88:89], v[28:29], v[68:69], v[72:73]
	v_lshlrev_b32_e32 v66, 16, v98
	v_and_b32_e32 v67, 0xffff0000, v98
	s_waitcnt vmcnt(2)
	v_pk_fma_f32 v[86:87], v[34:35], v[82:83], v[86:87]
	v_pk_fma_f32 v[88:89], v[32:33], v[78:79], v[88:89]
	v_lshlrev_b32_e32 v72, 16, v99
	v_and_b32_e32 v73, 0xffff0000, v99
	s_waitcnt vmcnt(1)
	v_pk_fma_f32 v[86:87], v[38:39], v[58:59], v[86:87]
	v_pk_fma_f32 v[88:89], v[36:37], v[56:57], v[88:89]
	s_waitcnt vmcnt(0)
; __device__ __forceinline__ void conv_group(const bf16_t* VC, size_t vrow0  , int tvalid0  , const float* hist,
;                                            const float* cw, const float* cb, const float* lg, const float* lb, bf16_t* MIX, size_t orow0, int lane) {
;     ...
;     const f32x4 gg = *(const f32x4*)(lg + c4), bb = *(const f32x4*)(lb + c4);
; #pragma unroll
;     for (int jj = 0; jj < 4; ++jj) { const f32x4 a = acc[jj];
;         const float mean = wave_sum((a[0] + a[1]) + (a[2] + a[3])) * (1.0f / 256.0f);
;         const f32x4 dl = a - mean; const float var = wave_sum((dl[0] * dl[0] + dl[1] * dl[1]) + (dl[2] * dl[2] + dl[3] * dl[3])) * (1.0f / 256.0f);
;         const float rstd = 1.0f / sqrtf(var + EPS); f32x4 y = dl * rstd * gg + bb;
	v_pk_fma_f32 v[86:87], v[42:43], v[72:73], v[86:87]
	v_pk_fma_f32 v[138:139], v[40:41], v[66:67], v[88:89]
	v_mov_b32_e32 v91, v87
	v_pk_mov_b32 v[88:89], v[138:139], v[86:87] op_sel:[1,0]
	v_mov_b32_e32 v90, v138
	v_pk_add_f32 v[88:89], v[88:89], v[90:91]
	v_pk_fma_f32 v[98:99], v[44:45], v[124:125], v[134:135]
	v_add_f32_e32 v140, v88, v89
	ds_swizzle_b32 v141, v140 offset:swizzle(SWAP,1)
	v_pk_fma_f32 v[88:89], v[44:45], v[112:113], v[118:119]
	v_pk_fma_f32 v[44:45], v[44:45], v[120:121], v[128:129]
	v_pk_fma_f32 v[88:89], v[48:49], v[124:125], v[88:89]
	v_pk_fma_f32 v[90:91], v[46:47], v[126:127], v[132:133]
	s_waitcnt lgkmcnt(0)
	v_add_f32_e32 v118, v140, v141
	ds_swizzle_b32 v119, v118 offset:swizzle(SWAP,2)
	v_pk_fma_f32 v[46:47], v[46:47], v[122:123], v[136:137]
	v_pk_fma_f32 v[112:113], v[50:51], v[126:127], v[130:131]
	v_pk_fma_f32 v[90:91], v[50:51], v[122:123], v[90:91]
	v_pk_fma_f32 v[98:99], v[48:49], v[120:121], v[98:99]
	s_waitcnt lgkmcnt(0)
	v_add_f32_e32 v124, v118, v119
	ds_swizzle_b32 v125, v124 offset:swizzle(SWAP,4)
	v_pk_fma_f32 v[118:119], v[48:49], v[114:115], v[44:45]
	v_pk_fma_f32 v[46:47], v[50:51], v[116:117], v[46:47]
	v_pk_fma_f32 v[88:89], v[52:53], v[120:121], v[88:89]
	v_lshl_add_u64 v[48:49], s[12:13], 0, v[74:75]
	s_waitcnt lgkmcnt(0)
	v_add_f32_e32 v44, v124, v125
	ds_swizzle_b32 v45, v44 offset:swizzle(SWAP,8)
	v_pk_fma_f32 v[112:113], v[54:55], v[122:123], v[112:113]
	v_pk_fma_f32 v[90:91], v[54:55], v[116:117], v[90:91]
	v_pk_fma_f32 v[54:55], v[54:55], v[110:111], v[46:47]
	global_load_dwordx4 v[48:51], v[48:49], off
	s_waitcnt lgkmcnt(0)
	v_add_f32_e32 v120, v44, v45
	v_lshl_add_u64 v[44:45], s[0:1], 0, v[74:75]
	global_load_dwordx4 v[44:47], v[44:45], off
	ds_swizzle_b32 v121, v120 offset:swizzle(SWAP,16)
	v_pk_fma_f32 v[88:89], v[0:1], v[114:115], v[88:89]
	v_pk_fma_f32 v[98:99], v[52:53], v[114:115], v[98:99]
	v_pk_fma_f32 v[88:89], v[4:5], v[108:109], v[88:89]
	v_pk_fma_f32 v[52:53], v[52:53], v[108:109], v[118:119]
	s_waitcnt lgkmcnt(0)
	v_add_f32_e32 v74, v120, v121
	v_mov_b32_e32 v75, v74
	s_nop 1
	v_permlane32_swap_b32 v74, v75
	s_nop 1
	v_pk_fma_f32 v[88:89], v[8:9], v[100:101], v[88:89]
	v_add_f32_e32 v74, v74, v75
	v_fmac_f32_e32 v87, 0xbb800000, v74
	v_fmac_f32_e32 v139, 0xbb800000, v74
	v_fmamk_f32 v86, v74, 0xbb800000, v86
	v_fmamk_f32 v138, v74, 0xbb800000, v138
	v_mul_f32_e32 v74, v139, v139
	v_mul_f32_e32 v75, v87, v87
	v_fmac_f32_e32 v74, v138, v138
	v_fmac_f32_e32 v75, v86, v86
	v_add_f32_e32 v120, v74, v75
	ds_swizzle_b32 v121, v120 offset:swizzle(SWAP,1)
	v_pk_fma_f32 v[74:75], v[2:3], v[116:117], v[112:113]
	v_pk_fma_f32 v[88:89], v[12:13], v[104:105], v[88:89]
	v_pk_fma_f32 v[74:75], v[6:7], v[110:111], v[74:75]
	v_pk_fma_f32 v[88:89], v[16:17], v[80:81], v[88:89]
	s_waitcnt lgkmcnt(0)
	v_add_f32_e32 v112, v120, v121
	ds_swizzle_b32 v113, v112 offset:swizzle(SWAP,2)
	v_pk_fma_f32 v[74:75], v[10:11], v[102:103], v[74:75]
	v_pk_fma_f32 v[88:89], v[20:21], v[96:97], v[88:89]
	v_pk_fma_f32 v[74:75], v[14:15], v[106:107], v[74:75]
	v_pk_fma_f32 v[88:89], v[24:25], v[68:69], v[88:89]
	s_waitcnt lgkmcnt(0)
	v_add_f32_e32 v112, v112, v113
	ds_swizzle_b32 v113, v112 offset:swizzle(SWAP,4)
	v_pk_fma_f32 v[74:75], v[18:19], v[92:93], v[74:75]
	v_pk_fma_f32 v[88:89], v[28:29], v[78:79], v[88:89]
	v_pk_fma_f32 v[74:75], v[22:23], v[84:85], v[74:75]
	v_pk_fma_f32 v[114:115], v[32:33], v[56:57], v[88:89]
	s_waitcnt lgkmcnt(0)
	v_add_f32_e32 v112, v112, v113
	ds_swizzle_b32 v113, v112 offset:swizzle(SWAP,8)
	v_pk_fma_f32 v[74:75], v[26:27], v[76:77], v[74:75]
	v_and_b32_e32 v89, 0xffff0000, v95
	v_pk_fma_f32 v[74:75], v[30:31], v[82:83], v[74:75]
	v_pk_fma_f32 v[98:99], v[0:1], v[108:109], v[98:99]
	s_waitcnt lgkmcnt(0)
	v_add_f32_e32 v116, v112, v113
	ds_swizzle_b32 v117, v116 offset:swizzle(SWAP,16)
	v_pk_fma_f32 v[112:113], v[34:35], v[58:59], v[74:75]
	v_lshlrev_b32_e32 v74, 16, v94
	v_pk_fma_f32 v[98:99], v[4:5], v[100:101], v[98:99]
	v_pk_fma_f32 v[90:91], v[2:3], v[110:111], v[90:91]
	s_waitcnt lgkmcnt(0)
	v_add_f32_e32 v75, v116, v117
	v_mov_b32_e32 v88, v75
	s_nop 1
	v_permlane32_swap_b32 v75, v88
	s_nop 1
	v_pk_fma_f32 v[98:99], v[8:9], v[104:105], v[98:99]
	v_add_f32_e32 v75, v75, v88
	v_fmamk_f32 v75, v75, 0x3b800000, v202
	v_mul_f32_e32 v88, 0x4f800000, v75
	v_cmp_gt_f32_e32 vcc, s95, v75
	v_pk_fma_f32 v[98:99], v[12:13], v[80:81], v[98:99]
	v_pk_fma_f32 v[90:91], v[6:7], v[102:103], v[90:91]
	v_cndmask_b32_e32 v116, v75, v88, vcc
	v_sqrt_f32_e32 v117, v116
	v_and_b32_e32 v75, 0xffff0000, v94
	v_lshlrev_b32_e32 v88, 16, v95
	v_pk_fma_f32 v[98:99], v[16:17], v[96:97], v[98:99]
	v_add_u32_e32 v94, -1, v117
	v_fma_f32 v95, -v94, v117, v116
	v_cmp_ge_f32_e64 s[0:1], 0, v95
	v_add_u32_e32 v95, 1, v117
	v_pk_fma_f32 v[98:99], v[20:21], v[68:69], v[98:99]
	v_cndmask_b32_e64 v94, v117, v94, s[0:1]
	v_fma_f32 v117, -v95, v117, v116
	v_cmp_lt_f32_e64 s[0:1], 0, v117
	v_pk_fma_f32 v[98:99], v[24:25], v[78:79], v[98:99]
	v_pk_fma_f32 v[90:91], v[10:11], v[106:107], v[90:91]
	v_cndmask_b32_e64 v94, v94, v95, s[0:1]
	v_mul_f32_e32 v95, 0x37800000, v94
	v_cndmask_b32_e32 v94, v94, v95, vcc
	v_cmp_class_f32_e32 vcc, v116, v203
	v_pk_fma_f32 v[98:99], v[28:29], v[56:57], v[98:99]
	v_pk_fma_f32 v[90:91], v[14:15], v[92:93], v[90:91]
	v_cndmask_b32_e32 v116, v94, v116, vcc
	v_div_scale_f32 v117, s[0:1], v116, v116, 1.0
	v_rcp_f32_e32 v118, v117
	v_pk_fma_f32 v[94:95], v[38:39], v[72:73], v[112:113]
	v_pk_fma_f32 v[112:113], v[36:37], v[66:67], v[114:115]
	v_pk_fma_f32 v[94:95], v[42:43], v[88:89], v[94:95]
	v_fma_f32 v114, -v117, v118, 1.0
	v_fmac_f32_e32 v118, v114, v118
	v_div_scale_f32 v114, vcc, 1.0, v116, 1.0
	v_mul_f32_e32 v115, v114, v118
	v_fma_f32 v119, -v117, v115, v114
	v_fmac_f32_e32 v115, v119, v118
	v_fma_f32 v114, -v117, v115, v114
	v_div_fmas_f32 v114, v114, v118, v115
	v_div_fixup_f32 v114, v114, v116, 1.0
	v_pk_mul_f32 v[116:117], v[138:139], v[114:115] op_sel_hi:[1,0]
	v_pk_fma_f32 v[112:113], v[40:41], v[74:75], v[112:113]
	s_waitcnt vmcnt(0)
; __device__ __forceinline__ unsigned cvt_pk_bf16(float lo, float hi) { const f32x2_t v = {lo, hi}; const bf16x2_t b = __builtin_convertvector(v, bf16x2_t); return __builtin_bit_cast(unsigned, b); }
; __device__ __forceinline__ float sigmoidf_(float x) { return __builtin_amdgcn_rcpf(1.0f + __expf(-x)); }
; __device__ __forceinline__ void conv_group(const bf16_t* VC, size_t vrow0  , int tvalid0  , const float* hist,
;                                            const float* cw, const float* cb, const float* lg, const float* lb, bf16_t* MIX, size_t orow0, int lane) {
;     ...
;     for (int jj = 0; jj < 4; ++jj) { const f32x4 a = acc[jj];
;         const float mean = wave_sum((a[0] + a[1]) + (a[2] + a[3])) * (1.0f / 256.0f);
;         const f32x4 dl = a - mean; const float var = wave_sum((dl[0] * dl[0] + dl[1] * dl[1]) + (dl[2] * dl[2] + dl[3] * dl[3])) * (1.0f / 256.0f);
;         const float rstd = 1.0f / sqrtf(var + EPS); f32x4 y = dl * rstd * gg + bb;
; #pragma unroll
;         for (int i = 0; i < 4; ++i) y[i] = y[i] * sigmoidf_(y[i]);
;         *(u32x2*)(MIX + (orow0 + jj) * 1024 + 768 + c4) = (u32x2){cvt_pk_bf16(y[0], y[1]), cvt_pk_bf16(y[2], y[3])}; }
	v_pk_fma_f32 v[116:117], v[44:45], v[116:117], v[48:49]
	v_mov_b32_e32 v118, v112
	v_mul_f32_e32 v115, 0xbfb8aa3b, v116
	v_exp_f32_e32 v115, v115
	v_mov_b32_e32 v119, v95
	s_lshl_b64 s[0:1], s[10:11], 11
	s_add_u32 s0, s4, s0
	v_pk_mul_f32 v[86:87], v[86:87], v[114:115] op_sel_hi:[1,0]
	v_mul_f32_e32 v114, 0xbfb8aa3b, v117
	v_add_f32_e32 v120, 1.0, v115
	v_exp_f32_e32 v121, v114
	v_pk_mov_b32 v[114:115], v[112:113], v[94:95] op_sel:[1,0]
	v_pk_fma_f32 v[86:87], v[46:47], v[86:87], v[50:51]
	v_pk_add_f32 v[114:115], v[114:115], v[118:119]
	v_add_f32_e32 v119, 1.0, v121
	v_add_f32_e32 v115, v114, v115
	ds_swizzle_b32 v118, v115 offset:swizzle(SWAP,1)
	v_rcp_f32_e32 v114, v120
	v_mul_f32_e32 v120, 0xbfb8aa3b, v86
	v_exp_f32_e32 v120, v120
	s_addc_u32 s1, s5, s1
	s_waitcnt lgkmcnt(0)
	v_add_f32_e32 v118, v115, v118
	ds_swizzle_b32 v121, v118 offset:swizzle(SWAP,2)
	v_rcp_f32_e32 v115, v119
	v_add_f32_e32 v119, 1.0, v120
	v_mul_f32_e32 v120, 0xbfb8aa3b, v87
	v_exp_f32_e32 v120, v120
	s_waitcnt lgkmcnt(0)
	v_add_f32_e32 v121, v118, v121
	ds_swizzle_b32 v122, v121 offset:swizzle(SWAP,4)
	v_pk_mul_f32 v[114:115], v[116:117], v[114:115]
	v_rcp_f32_e32 v118, v119
	v_add_f32_e32 v119, 1.0, v120
	v_rcp_f32_e32 v119, v119
	s_waitcnt lgkmcnt(0)
	v_add_f32_e32 v116, v121, v122
	ds_swizzle_b32 v117, v116 offset:swizzle(SWAP,8)
	v_cvt_pk_bf16_f32 v114, v114, v115
	v_pk_mul_f32 v[86:87], v[86:87], v[118:119]
	v_pk_fma_f32 v[98:99], v[32:33], v[66:67], v[98:99]
	v_cvt_pk_bf16_f32 v115, v86, v87
	s_waitcnt lgkmcnt(0)
	v_add_f32_e32 v116, v116, v117
	ds_swizzle_b32 v117, v116 offset:swizzle(SWAP,16)
	v_lshl_add_u64 v[86:87], v[60:61], 1, s[0:1]
	global_store_dwordx2 v[86:87], v[114:115], off offset:1536
	v_pk_fma_f32 v[110:111], v[36:37], v[74:75], v[98:99]
	v_pk_fma_f32 v[90:91], v[18:19], v[84:85], v[90:91]
	s_waitcnt lgkmcnt(0)
	v_add_f32_e32 v114, v116, v117
	v_mov_b32_e32 v115, v114
	s_nop 1
	v_permlane32_swap_b32 v114, v115
	s_nop 1
	v_pk_fma_f32 v[90:91], v[22:23], v[76:77], v[90:91]
	v_add_f32_e32 v114, v114, v115
	v_fmac_f32_e32 v95, 0xbb800000, v114
	v_fmac_f32_e32 v113, 0xbb800000, v114
	v_fmamk_f32 v94, v114, 0xbb800000, v94
	v_fmamk_f32 v112, v114, 0xbb800000, v112
	v_mul_f32_e32 v114, v113, v113
	v_mul_f32_e32 v115, v95, v95
	v_fmac_f32_e32 v114, v112, v112
	v_fmac_f32_e32 v115, v94, v94
	v_add_f32_e32 v114, v114, v115
	ds_swizzle_b32 v115, v114 offset:swizzle(SWAP,1)
	v_pk_fma_f32 v[90:91], v[26:27], v[82:83], v[90:91]
	v_pk_fma_f32 v[0:1], v[0:1], v[100:101], v[52:53]
	v_pk_fma_f32 v[90:91], v[30:31], v[58:59], v[90:91]
	v_pk_fma_f32 v[0:1], v[4:5], v[104:105], v[0:1]
	s_waitcnt lgkmcnt(0)
	v_add_f32_e32 v108, v114, v115
	ds_swizzle_b32 v109, v108 offset:swizzle(SWAP,2)
	v_pk_fma_f32 v[90:91], v[34:35], v[72:73], v[90:91]
	v_pk_fma_f32 v[2:3], v[2:3], v[102:103], v[54:55]
	v_pk_fma_f32 v[90:91], v[38:39], v[88:89], v[90:91]
	v_pk_fma_f32 v[0:1], v[8:9], v[80:81], v[0:1]
	s_waitcnt lgkmcnt(0)
	v_add_f32_e32 v108, v108, v109
	ds_swizzle_b32 v109, v108 offset:swizzle(SWAP,4)
	v_pk_fma_f32 v[2:3], v[6:7], v[106:107], v[2:3]
	v_pk_fma_f32 v[0:1], v[12:13], v[96:97], v[0:1]
	v_pk_fma_f32 v[2:3], v[10:11], v[92:93], v[2:3]
	v_pk_fma_f32 v[0:1], v[16:17], v[68:69], v[0:1]
	s_waitcnt lgkmcnt(0)
	v_add_f32_e32 v108, v108, v109
	ds_swizzle_b32 v109, v108 offset:swizzle(SWAP,8)
	v_pk_fma_f32 v[0:1], v[20:21], v[78:79], v[0:1]
	v_pk_fma_f32 v[2:3], v[14:15], v[84:85], v[2:3]
	v_pk_fma_f32 v[0:1], v[24:25], v[56:57], v[0:1]
	v_pk_fma_f32 v[2:3], v[18:19], v[76:77], v[2:3]
	s_waitcnt lgkmcnt(0)
	v_add_f32_e32 v108, v108, v109
	ds_swizzle_b32 v109, v108 offset:swizzle(SWAP,16)
	v_pk_fma_f32 v[0:1], v[28:29], v[66:67], v[0:1]
	v_pk_fma_f32 v[2:3], v[22:23], v[82:83], v[2:3]
	v_pk_fma_f32 v[0:1], v[32:33], v[74:75], v[0:1]
	v_pk_fma_f32 v[2:3], v[26:27], v[58:59], v[2:3]
	s_waitcnt lgkmcnt(0)
	v_add_f32_e32 v98, v108, v109
	v_mov_b32_e32 v99, v98
	s_nop 1
	v_permlane32_swap_b32 v98, v99
	s_nop 1
	v_lshlrev_b32_e32 v108, 16, v71
	v_add_f32_e32 v98, v98, v99
	v_fmamk_f32 v98, v98, 0x3b800000, v202
	v_mul_f32_e32 v99, 0x4f800000, v98
	v_cmp_gt_f32_e32 vcc, s95, v98
	v_pk_fma_f32 v[2:3], v[30:31], v[72:73], v[2:3]
	s_nop 0
	v_cndmask_b32_e32 v109, v98, v99, vcc
	v_sqrt_f32_e32 v114, v109
	v_lshlrev_b32_e32 v98, 16, v70
	v_and_b32_e32 v99, 0xffff0000, v70
	v_pk_fma_f32 v[2:3], v[34:35], v[88:89], v[2:3]
	v_add_u32_e32 v70, -1, v114
	v_fma_f32 v115, -v70, v114, v109
	v_cmp_ge_f32_e64 s[0:1], 0, v115
	v_add_u32_e32 v115, 1, v114
	s_nop 0
	v_cndmask_b32_e64 v70, v114, v70, s[0:1]
	v_fma_f32 v114, -v115, v114, v109
	v_cmp_lt_f32_e64 s[0:1], 0, v114
	s_nop 1
	v_cndmask_b32_e64 v70, v70, v115, s[0:1]
	v_mul_f32_e32 v114, 0x37800000, v70
	v_cndmask_b32_e32 v70, v70, v114, vcc
	v_cmp_class_f32_e32 vcc, v109, v203
	s_nop 1
	v_cndmask_b32_e32 v114, v70, v109, vcc
	v_div_scale_f32 v115, s[0:1], v114, v114, 1.0
	v_rcp_f32_e32 v116, v115
	v_and_b32_e32 v109, 0xffff0000, v71
	v_pk_fma_f32 v[70:71], v[42:43], v[108:109], v[90:91]
	v_pk_fma_f32 v[90:91], v[40:41], v[98:99], v[110:111]
	v_fma_f32 v110, -v115, v116, 1.0
	v_fmac_f32_e32 v116, v110, v116
	v_div_scale_f32 v110, vcc, 1.0, v114, 1.0
	v_mul_f32_e32 v111, v110, v116
	v_fma_f32 v117, -v115, v111, v110
	v_fmac_f32_e32 v111, v117, v116
	v_fma_f32 v110, -v115, v111, v110
	v_div_fmas_f32 v110, v110, v116, v111
	v_div_fixup_f32 v110, v110, v114, 1.0
	v_pk_mul_f32 v[112:113], v[112:113], v[110:111] op_sel_hi:[1,0]
	v_pk_mul_f32 v[94:95], v[94:95], v[110:111] op_sel_hi:[1,0]
	v_pk_fma_f32 v[110:111], v[44:45], v[112:113], v[48:49]
	v_mov_b32_e32 v114, v90
	v_mul_f32_e32 v112, 0xbfb8aa3b, v110
	v_exp_f32_e32 v116, v112
	v_pk_mov_b32 v[112:113], v[90:91], v[70:71] op_sel:[1,0]
	v_mov_b32_e32 v115, v71
	v_pk_add_f32 v[112:113], v[112:113], v[114:115]
	v_add_f32_e32 v114, 1.0, v116
	v_add_f32_e32 v112, v112, v113
	ds_swizzle_b32 v113, v112 offset:swizzle(SWAP,1)
	v_mul_f32_e32 v115, 0xbfb8aa3b, v111
	v_exp_f32_e32 v115, v115
	v_pk_fma_f32 v[94:95], v[46:47], v[94:95], v[50:51]
	v_pk_fma_f32 v[2:3], v[38:39], v[108:109], v[2:3]
	s_waitcnt lgkmcnt(0)
; __device__ __forceinline__ unsigned cvt_pk_bf16(float lo, float hi) { const f32x2_t v = {lo, hi}; const bf16x2_t b = __builtin_convertvector(v, bf16x2_t); return __builtin_bit_cast(unsigned, b); }
; __device__ __forceinline__ float sigmoidf_(float x) { return __builtin_amdgcn_rcpf(1.0f + __expf(-x)); }
; __device__ __forceinline__ void conv_group(const bf16_t* VC, size_t vrow0  , int tvalid0  , const float* hist,
;                                            const float* cw, const float* cb, const float* lg, const float* lb, bf16_t* MIX, size_t orow0, int lane) {
;     ...
;     for (int jj = 0; jj < 4; ++jj) { const f32x4 a = acc[jj];
;         const float mean = wave_sum((a[0] + a[1]) + (a[2] + a[3])) * (1.0f / 256.0f);
;         const f32x4 dl = a - mean; const float var = wave_sum((dl[0] * dl[0] + dl[1] * dl[1]) + (dl[2] * dl[2] + dl[3] * dl[3])) * (1.0f / 256.0f);
;         const float rstd = 1.0f / sqrtf(var + EPS); f32x4 y = dl * rstd * gg + bb;
; #pragma unroll
;         for (int i = 0; i < 4; ++i) y[i] = y[i] * sigmoidf_(y[i]);
;         *(u32x2*)(MIX + (orow0 + jj) * 1024 + 768 + c4) = (u32x2){cvt_pk_bf16(y[0], y[1]), cvt_pk_bf16(y[2], y[3])}; }
	v_add_f32_e32 v113, v112, v113
	ds_swizzle_b32 v116, v113 offset:swizzle(SWAP,2)
	v_rcp_f32_e32 v112, v114
	v_add_f32_e32 v114, 1.0, v115
	v_mul_f32_e32 v115, 0xbfb8aa3b, v94
	v_exp_f32_e32 v115, v115
	s_waitcnt lgkmcnt(0)
	v_add_f32_e32 v116, v113, v116
	ds_swizzle_b32 v117, v116 offset:swizzle(SWAP,4)
	v_rcp_f32_e32 v113, v114
	v_add_f32_e32 v114, 1.0, v115
	v_mul_f32_e32 v115, 0xbfb8aa3b, v95
	v_exp_f32_e32 v115, v115
	s_waitcnt lgkmcnt(0)
	v_add_f32_e32 v116, v116, v117
	ds_swizzle_b32 v117, v116 offset:swizzle(SWAP,8)
	v_pk_mul_f32 v[110:111], v[110:111], v[112:113]
	v_add_f32_e32 v115, 1.0, v115
	v_rcp_f32_e32 v114, v114
	v_rcp_f32_e32 v115, v115
	s_waitcnt lgkmcnt(0)
	v_add_f32_e32 v112, v116, v117
	ds_swizzle_b32 v113, v112 offset:swizzle(SWAP,16)
	v_cvt_pk_bf16_f32 v110, v110, v111
	v_pk_mul_f32 v[94:95], v[94:95], v[114:115]
	s_nop 0
	v_cvt_pk_bf16_f32 v111, v94, v95
	s_waitcnt lgkmcnt(0)
	v_add_f32_e32 v94, v112, v113
	v_mov_b32_e32 v95, v94
	global_store_dwordx2 v[86:87], v[110:111], off offset:3584
	s_nop 1
	v_permlane32_swap_b32 v94, v95
	s_nop 1
	s_nop 0
	v_add_f32_e32 v94, v94, v95
	v_fmac_f32_e32 v71, 0xbb800000, v94
	v_fmac_f32_e32 v91, 0xbb800000, v94
	v_fmamk_f32 v70, v94, 0xbb800000, v70
	v_fmamk_f32 v90, v94, 0xbb800000, v90
	v_mul_f32_e32 v94, v91, v91
	v_mul_f32_e32 v95, v71, v71
	v_fmac_f32_e32 v94, v90, v90
	v_fmac_f32_e32 v95, v70, v70
	v_add_f32_e32 v94, v94, v95
	ds_swizzle_b32 v95, v94 offset:swizzle(SWAP,1)
	s_waitcnt lgkmcnt(0)
	v_add_f32_e32 v4, v94, v95
	ds_swizzle_b32 v5, v4 offset:swizzle(SWAP,2)
	s_waitcnt lgkmcnt(0)
	v_add_f32_e32 v4, v4, v5
	ds_swizzle_b32 v5, v4 offset:swizzle(SWAP,4)
	s_waitcnt lgkmcnt(0)
	v_add_f32_e32 v4, v4, v5
	ds_swizzle_b32 v5, v4 offset:swizzle(SWAP,8)
	s_waitcnt lgkmcnt(0)
	v_add_f32_e32 v6, v4, v5
	ds_swizzle_b32 v7, v6 offset:swizzle(SWAP,16)
	v_pk_fma_f32 v[4:5], v[36:37], v[98:99], v[0:1]
	s_waitcnt lgkmcnt(0)
	v_add_f32_e32 v0, v6, v7
	v_mov_b32_e32 v1, v0
	s_nop 1
	v_permlane32_swap_b32 v0, v1
	s_nop 1
	v_lshlrev_b32_e32 v6, 16, v64
	v_add_f32_e32 v0, v0, v1
	v_fmamk_f32 v0, v0, 0x3b800000, v202
	v_mul_f32_e32 v1, 0x4f800000, v0
	v_cmp_gt_f32_e32 vcc, s95, v0
	v_and_b32_e32 v7, 0xffff0000, v64
	s_nop 0
	v_cndmask_b32_e32 v1, v0, v1, vcc
	v_sqrt_f32_e32 v8, v1
	v_lshlrev_b32_e32 v0, 16, v65
	v_add_u32_e32 v9, -1, v8
	v_fma_f32 v10, -v9, v8, v1
	v_cmp_ge_f32_e64 s[0:1], 0, v10
	v_add_u32_e32 v10, 1, v8
	s_nop 0
	v_cndmask_b32_e64 v9, v8, v9, s[0:1]
	v_fma_f32 v8, -v10, v8, v1
	v_cmp_lt_f32_e64 s[0:1], 0, v8
	s_nop 1
	v_cndmask_b32_e64 v8, v9, v10, s[0:1]
	v_mul_f32_e32 v9, 0x37800000, v8
	v_cndmask_b32_e32 v8, v8, v9, vcc
	v_cmp_class_f32_e32 vcc, v1, v203
	s_nop 1
	v_cndmask_b32_e32 v8, v8, v1, vcc
	v_div_scale_f32 v9, s[0:1], v8, v8, 1.0
	v_rcp_f32_e32 v10, v9
	v_and_b32_e32 v1, 0xffff0000, v65
	v_pk_fma_f32 v[0:1], v[42:43], v[0:1], v[2:3]
	v_pk_fma_f32 v[2:3], v[40:41], v[6:7], v[4:5]
	v_fma_f32 v4, -v9, v10, 1.0
	v_fmac_f32_e32 v10, v4, v10
	v_div_scale_f32 v4, vcc, 1.0, v8, 1.0
	v_mul_f32_e32 v5, v4, v10
	v_fma_f32 v6, -v9, v5, v4
	v_fmac_f32_e32 v5, v6, v10
	v_fma_f32 v4, -v9, v5, v4
	v_div_fmas_f32 v4, v4, v10, v5
	v_div_fixup_f32 v4, v4, v8, 1.0
	v_pk_mul_f32 v[6:7], v[90:91], v[4:5] op_sel_hi:[1,0]
	v_mov_b32_e32 v10, v2
	v_pk_fma_f32 v[6:7], v[44:45], v[6:7], v[48:49]
	v_mov_b32_e32 v11, v1
	v_mul_f32_e32 v8, 0xbfb8aa3b, v6
	v_exp_f32_e32 v12, v8
	v_mul_f32_e32 v8, 0xbfb8aa3b, v7
	v_exp_f32_e32 v13, v8
	v_pk_mov_b32 v[8:9], v[2:3], v[0:1] op_sel:[1,0]
	v_pk_mul_f32 v[4:5], v[70:71], v[4:5] op_sel_hi:[1,0]
	v_pk_add_f32 v[8:9], v[8:9], v[10:11]
	v_pk_fma_f32 v[4:5], v[46:47], v[4:5], v[50:51]
	v_add_f32_e32 v10, v8, v9
	ds_swizzle_b32 v11, v10 offset:swizzle(SWAP,1)
	v_add_f32_e32 v8, 1.0, v12
	v_mul_f32_e32 v12, 0xbfb8aa3b, v4
	v_add_f32_e32 v9, 1.0, v13
	v_exp_f32_e32 v12, v12
	s_waitcnt lgkmcnt(0)
; __device__ __forceinline__ unsigned cvt_pk_bf16(float lo, float hi) { const f32x2_t v = {lo, hi}; const bf16x2_t b = __builtin_convertvector(v, bf16x2_t); return __builtin_bit_cast(unsigned, b); }
; __device__ __forceinline__ float sigmoidf_(float x) { return __builtin_amdgcn_rcpf(1.0f + __expf(-x)); }
; __device__ __forceinline__ void conv_group(const bf16_t* VC, size_t vrow0  , int tvalid0  , const float* hist,
;                                            const float* cw, const float* cb, const float* lg, const float* lb, bf16_t* MIX, size_t orow0, int lane) {
;     ...
;     for (int jj = 0; jj < 4; ++jj) { const f32x4 a = acc[jj];
;         const float mean = wave_sum((a[0] + a[1]) + (a[2] + a[3])) * (1.0f / 256.0f);
;         const f32x4 dl = a - mean; const float var = wave_sum((dl[0] * dl[0] + dl[1] * dl[1]) + (dl[2] * dl[2] + dl[3] * dl[3])) * (1.0f / 256.0f);
;         const float rstd = 1.0f / sqrtf(var + EPS); f32x4 y = dl * rstd * gg + bb;
; #pragma unroll
;         for (int i = 0; i < 4; ++i) y[i] = y[i] * sigmoidf_(y[i]);
;         *(u32x2*)(MIX + (orow0 + jj) * 1024 + 768 + c4) = (u32x2){cvt_pk_bf16(y[0], y[1]), cvt_pk_bf16(y[2], y[3])}; }
	v_add_f32_e32 v10, v10, v11
	ds_swizzle_b32 v11, v10 offset:swizzle(SWAP,2)
	v_mul_f32_e32 v13, 0xbfb8aa3b, v5
	v_exp_f32_e32 v13, v13
	v_rcp_f32_e32 v8, v8
	v_rcp_f32_e32 v9, v9
	s_waitcnt lgkmcnt(0)
	v_add_f32_e32 v14, v10, v11
	ds_swizzle_b32 v15, v14 offset:swizzle(SWAP,4)
	v_add_f32_e32 v10, 1.0, v12
	v_add_f32_e32 v11, 1.0, v13
	v_rcp_f32_e32 v10, v10
	v_rcp_f32_e32 v11, v11
	s_waitcnt lgkmcnt(0)
	v_add_f32_e32 v12, v14, v15
	ds_swizzle_b32 v13, v12 offset:swizzle(SWAP,8)
	v_pk_mul_f32 v[6:7], v[6:7], v[8:9]
	v_pk_mul_f32 v[4:5], v[4:5], v[10:11]
	v_cvt_pk_bf16_f32 v6, v6, v7
	v_cvt_pk_bf16_f32 v7, v4, v5
	s_waitcnt lgkmcnt(0)
	v_add_f32_e32 v8, v12, v13
	ds_swizzle_b32 v9, v8 offset:swizzle(SWAP,16)
	v_add_co_u32_e32 v4, vcc, s81, v86
	s_nop 1
	v_addc_co_u32_e32 v5, vcc, 0, v87, vcc
	global_store_dwordx2 v[4:5], v[6:7], off offset:1536
	s_waitcnt lgkmcnt(0)
	v_add_f32_e32 v6, v8, v9
	v_mov_b32_e32 v7, v6
	s_nop 1
	v_permlane32_swap_b32 v6, v7
	s_nop 1
	s_nop 0
	v_add_f32_e32 v6, v6, v7
	v_fmac_f32_e32 v1, 0xbb800000, v6
	v_fmac_f32_e32 v3, 0xbb800000, v6
	v_fmamk_f32 v0, v6, 0xbb800000, v0
	v_fmamk_f32 v2, v6, 0xbb800000, v2
	v_mul_f32_e32 v6, v3, v3
	v_mul_f32_e32 v7, v1, v1
	v_fmac_f32_e32 v6, v2, v2
	v_fmac_f32_e32 v7, v0, v0
	v_add_f32_e32 v6, v6, v7
	ds_swizzle_b32 v7, v6 offset:swizzle(SWAP,1)
	s_waitcnt lgkmcnt(0)
	v_add_f32_e32 v6, v6, v7
	ds_swizzle_b32 v7, v6 offset:swizzle(SWAP,2)
	s_waitcnt lgkmcnt(0)
	v_add_f32_e32 v6, v6, v7
	ds_swizzle_b32 v7, v6 offset:swizzle(SWAP,4)
	s_waitcnt lgkmcnt(0)
	v_add_f32_e32 v6, v6, v7
	ds_swizzle_b32 v7, v6 offset:swizzle(SWAP,8)
	s_waitcnt lgkmcnt(0)
	v_add_f32_e32 v6, v6, v7
	ds_swizzle_b32 v7, v6 offset:swizzle(SWAP,16)
	s_waitcnt lgkmcnt(0)
	v_add_f32_e32 v6, v6, v7
	v_mov_b32_e32 v7, v6
	s_nop 1
	v_permlane32_swap_b32 v6, v7
	s_nop 1
	s_nop 0
	v_add_f32_e32 v6, v6, v7
	v_fmamk_f32 v6, v6, 0x3b800000, v202
	v_mul_f32_e32 v7, 0x4f800000, v6
	v_cmp_gt_f32_e32 vcc, s95, v6
	s_nop 1
	v_cndmask_b32_e32 v6, v6, v7, vcc
	v_sqrt_f32_e32 v7, v6
	s_nop 0
	v_add_u32_e32 v8, -1, v7
	v_fma_f32 v9, -v8, v7, v6
	v_cmp_ge_f32_e64 s[0:1], 0, v9
	v_add_u32_e32 v9, 1, v7
	s_nop 0
	v_cndmask_b32_e64 v8, v7, v8, s[0:1]
	v_fma_f32 v7, -v9, v7, v6
	v_cmp_lt_f32_e64 s[0:1], 0, v7
	s_nop 1
	v_cndmask_b32_e64 v7, v8, v9, s[0:1]
	v_mul_f32_e32 v8, 0x37800000, v7
	v_cndmask_b32_e32 v7, v7, v8, vcc
	v_cmp_class_f32_e32 vcc, v6, v203
	s_nop 1
	v_cndmask_b32_e32 v6, v7, v6, vcc
	v_div_scale_f32 v7, s[0:1], v6, v6, 1.0
	v_rcp_f32_e32 v8, v7
	s_nop 0
	v_fma_f32 v9, -v7, v8, 1.0
	v_fmac_f32_e32 v8, v9, v8
	v_div_scale_f32 v9, vcc, 1.0, v6, 1.0
	v_mul_f32_e32 v10, v9, v8
	v_fma_f32 v11, -v7, v10, v9
	v_fmac_f32_e32 v10, v11, v8
	v_fma_f32 v7, -v7, v10, v9
	v_div_fmas_f32 v7, v7, v8, v10
	v_div_fixup_f32 v6, v7, v6, 1.0
	v_pk_mul_f32 v[2:3], v[2:3], v[6:7] op_sel_hi:[1,0]
	v_pk_mul_f32 v[0:1], v[0:1], v[6:7] op_sel_hi:[1,0]
	v_pk_fma_f32 v[2:3], v[44:45], v[2:3], v[48:49]
	v_pk_fma_f32 v[0:1], v[46:47], v[0:1], v[50:51]
	v_mul_f32_e32 v6, 0xbfb8aa3b, v2
	v_mul_f32_e32 v7, 0xbfb8aa3b, v3
	v_mul_f32_e32 v8, 0xbfb8aa3b, v0
	v_mul_f32_e32 v9, 0xbfb8aa3b, v1
	v_exp_f32_e32 v6, v6
	v_exp_f32_e32 v7, v7
	v_exp_f32_e32 v8, v8
	v_exp_f32_e32 v9, v9
	v_add_f32_e32 v6, 1.0, v6
	v_add_f32_e32 v7, 1.0, v7
	v_add_f32_e32 v8, 1.0, v8
	v_add_f32_e32 v9, 1.0, v9
	v_rcp_f32_e32 v6, v6
	v_rcp_f32_e32 v7, v7
	v_rcp_f32_e32 v8, v8
	v_rcp_f32_e32 v9, v9
	v_pk_mul_f32 v[2:3], v[2:3], v[6:7]
	s_nop 0
	v_cvt_pk_bf16_f32 v2, v2, v3
	v_pk_mul_f32 v[0:1], v[0:1], v[8:9]
	s_nop 0
	v_cvt_pk_bf16_f32 v3, v0, v1
	global_store_dwordx2 v[4:5], v[2:3], off offset:3584
	s_branch .LBB0_1163

;     __device__ __forceinline__ void operator()(const Acc& acc, const Unit& u, int wr, int wc, int fr, int fq) const {
; #pragma unroll
;         for (int ai = 0; ai < 2; ++ai)
; #pragma unroll
;             for (int m = 0; m < 4; ++m) { const int row = u.pm * 256 + ai * 128 + wr * 64 + m * 16 + fr;
;                 const float* base = xp ? (row < MP ? xp + (size_t)row * D : xs + (size_t)(row - MP) * D) : X + (size_t)row * D;
;                 const float* gp = gate + (size_t)mod_row(row) * 6144;
; #pragma unroll
;                 for (int bj = 0; bj < 2; ++bj)
; #pragma unroll
;                     for (int n = 0; n < 2; ++n) { const int col = u.pn * 256 + bj * 128 + wc * 32 + n * 16 + fq * 4;
;                         const f32x4 ga = *(const f32x4*)(gp + col) * acc[ai][bj][m][n];
;                         if (u.split) { *(f32x4*)(part + ((size_t)(u.k0 >> 8) * MS + (row - MP)) * D + col) = ga;
;                         } else *(f32x4*)(X + (size_t)row * D + col) = *(const f32x4*)(base + col) + ga; } }
;     }
.LBB0_1439:
	s_lshl_b32 s2, s4, 8
	s_add_i32 s2, s2, s55
	s_lshl_b32 s3, s36, 8
	s_add_i32 s3, s3, s56
	v_add_u32_e32 v207, s2, v155
	v_lshl_add_u32 v159, v156, 2, s3
	v_mov_b32_e32 v197, 0
	s_mov_b32 s70, 0x10000
	s_mov_b32 s71, 0
	s_mov_b32 s98, 0x50000
	s_mov_b32 s99, 0
	s_cmp_lg_u32 s63, 0
	s_cbranch_scc1 .Lepi_out_split
	s_mov_b32 s66, 0x10000
	s_mov_b32 s67, 0
	s_mov_b32 s68, 0x50000
	s_mov_b32 s69, 0
	v_lshlrev_b32_e32 v196, 12, v207
	v_lshl_add_u32 v196, v159, 2, v196
	v_lshrrev_b32_e32 v207, 12, v207
	v_lshlrev_b32_e32 v159, 2, v159
	v_mad_u32_u24 v144, v207, s80, v159
	v_mov_b32_e32 v145, 0
	v_lshl_add_u64 v[144:145], v[144:145], 0, s[18:19]
	global_load_dwordx4 v[188:191], v[144:145], off
	global_load_dwordx4 v[192:195], v[144:145], off offset:64
	global_load_dwordx4 v[128:131], v[144:145], off offset:512
	global_load_dwordx4 v[140:143], v[144:145], off offset:576
	v_lshl_add_u64 v[146:147], v[196:197], 0, s[16:17]
	s_cmp_lg_u64 s[22:23], 0
	s_cselect_b32 s2, s8, s16
	s_cselect_b32 s3, s9, s17
	v_lshl_add_u64 v[144:145], v[196:197], 0, s[2:3]
	global_load_dwordx4 v[208:211], v[144:145], off
	global_load_dwordx4 v[212:215], v[144:145], off offset:64
	global_load_dwordx4 v[216:219], v[144:145], off offset:512
	global_load_dwordx4 v[220:223], v[144:145], off offset:576
	v_lshl_add_u64 v[144:145], v[144:145], 0, s[66:67]
	global_load_dwordx4 v[224:227], v[144:145], off
	global_load_dwordx4 v[228:231], v[144:145], off offset:64
	global_load_dwordx4 v[232:235], v[144:145], off offset:512
	global_load_dwordx4 v[236:239], v[144:145], off offset:576
	v_lshl_add_u64 v[144:145], v[144:145], 0, s[66:67]
	global_load_dwordx4 v[240:243], v[144:145], off
	global_load_dwordx4 v[244:247], v[144:145], off offset:64
	global_load_dwordx4 v[248:251], v[144:145], off offset:512
	global_load_dwordx4 v[184:187], v[144:145], off offset:576
	v_lshl_add_u64 v[144:145], v[144:145], 0, s[66:67]
	s_waitcnt vmcnt(8)
	v_pk_mul_f32 v[126:127], v[126:127], v[190:191]
	v_pk_mul_f32 v[124:125], v[124:125], v[188:189]
	v_pk_add_f32 v[126:127], v[126:127], v[210:211]
	v_pk_add_f32 v[124:125], v[124:125], v[208:209]
	v_pk_mul_f32 v[122:123], v[122:123], v[194:195]
	v_pk_mul_f32 v[120:121], v[120:121], v[192:193]
	v_pk_add_f32 v[122:123], v[122:123], v[214:215]
	v_pk_add_f32 v[120:121], v[120:121], v[212:213]
	v_pk_mul_f32 v[118:119], v[118:119], v[130:131]
	v_pk_mul_f32 v[116:117], v[116:117], v[128:129]
	v_pk_add_f32 v[118:119], v[118:119], v[218:219]
	v_pk_add_f32 v[116:117], v[116:117], v[216:217]
	v_pk_mul_f32 v[114:115], v[114:115], v[142:143]
	v_pk_mul_f32 v[112:113], v[112:113], v[140:141]
	v_pk_add_f32 v[114:115], v[114:115], v[222:223]
	v_pk_add_f32 v[112:113], v[112:113], v[220:221]
	global_store_dwordx4 v[146:147], v[124:127], off
	global_store_dwordx4 v[146:147], v[120:123], off offset:64
	global_store_dwordx4 v[146:147], v[116:119], off offset:512
	global_store_dwordx4 v[146:147], v[112:115], off offset:576
	v_lshl_add_u64 v[146:147], v[146:147], 0, s[70:71]
	global_load_dwordx4 v[208:211], v[144:145], off
	global_load_dwordx4 v[212:215], v[144:145], off offset:64
	global_load_dwordx4 v[216:219], v[144:145], off offset:512
	global_load_dwordx4 v[220:223], v[144:145], off offset:576
	v_lshl_add_u64 v[144:145], v[144:145], 0, s[68:69]
	s_waitcnt vmcnt(12)
	v_pk_mul_f32 v[110:111], v[110:111], v[190:191]
	v_pk_mul_f32 v[108:109], v[108:109], v[188:189]
	v_pk_add_f32 v[110:111], v[110:111], v[226:227]
	v_pk_add_f32 v[108:109], v[108:109], v[224:225]
	v_pk_mul_f32 v[106:107], v[106:107], v[194:195]
	v_pk_mul_f32 v[104:105], v[104:105], v[192:193]
	v_pk_add_f32 v[106:107], v[106:107], v[230:231]
	v_pk_add_f32 v[104:105], v[104:105], v[228:229]
	v_pk_mul_f32 v[102:103], v[102:103], v[130:131]
	v_pk_mul_f32 v[100:101], v[100:101], v[128:129]
	v_pk_add_f32 v[102:103], v[102:103], v[234:235]
	v_pk_add_f32 v[100:101], v[100:101], v[232:233]
	v_pk_mul_f32 v[98:99], v[98:99], v[142:143]
	v_pk_mul_f32 v[96:97], v[96:97], v[140:141]
	v_pk_add_f32 v[98:99], v[98:99], v[238:239]
	v_pk_add_f32 v[96:97], v[96:97], v[236:237]
	global_store_dwordx4 v[146:147], v[108:111], off
	global_store_dwordx4 v[146:147], v[104:107], off offset:64
	global_store_dwordx4 v[146:147], v[100:103], off offset:512
	global_store_dwordx4 v[146:147], v[96:99], off offset:576
	v_lshl_add_u64 v[146:147], v[146:147], 0, s[70:71]
	global_load_dwordx4 v[224:227], v[144:145], off
	global_load_dwordx4 v[228:231], v[144:145], off offset:64
	global_load_dwordx4 v[232:235], v[144:145], off offset:512
	global_load_dwordx4 v[236:239], v[144:145], off offset:576
	v_lshl_add_u64 v[144:145], v[144:145], 0, s[66:67]
	s_waitcnt vmcnt(16)
	v_pk_mul_f32 v[94:95], v[94:95], v[190:191]
	v_pk_mul_f32 v[92:93], v[92:93], v[188:189]
	v_pk_add_f32 v[94:95], v[94:95], v[242:243]
	v_pk_add_f32 v[92:93], v[92:93], v[240:241]
	v_pk_mul_f32 v[90:91], v[90:91], v[194:195]
	v_pk_mul_f32 v[88:89], v[88:89], v[192:193]
	v_pk_add_f32 v[90:91], v[90:91], v[246:247]
	v_pk_add_f32 v[88:89], v[88:89], v[244:245]
	v_pk_mul_f32 v[86:87], v[86:87], v[130:131]
	v_pk_mul_f32 v[84:85], v[84:85], v[128:129]
	v_pk_add_f32 v[86:87], v[86:87], v[250:251]
	v_pk_add_f32 v[84:85], v[84:85], v[248:249]
	v_pk_mul_f32 v[82:83], v[82:83], v[142:143]
	v_pk_mul_f32 v[80:81], v[80:81], v[140:141]
	v_pk_add_f32 v[82:83], v[82:83], v[186:187]
	v_pk_add_f32 v[80:81], v[80:81], v[184:185]
	global_store_dwordx4 v[146:147], v[92:95], off
	global_store_dwordx4 v[146:147], v[88:91], off offset:64
	global_store_dwordx4 v[146:147], v[84:87], off offset:512
	global_store_dwordx4 v[146:147], v[80:83], off offset:576
	v_lshl_add_u64 v[146:147], v[146:147], 0, s[70:71]
	global_load_dwordx4 v[240:243], v[144:145], off
	global_load_dwordx4 v[244:247], v[144:145], off offset:64
	global_load_dwordx4 v[248:251], v[144:145], off offset:512
	global_load_dwordx4 v[184:187], v[144:145], off offset:576
	v_lshl_add_u64 v[144:145], v[144:145], 0, s[66:67]
	s_waitcnt vmcnt(16)
;     __device__ __forceinline__ void operator()(const Acc& acc, const Unit& u, int wr, int wc, int fr, int fq) const {
; #pragma unroll
;         for (int ai = 0; ai < 2; ++ai)
; #pragma unroll
;             for (int m = 0; m < 4; ++m) { const int row = u.pm * 256 + ai * 128 + wr * 64 + m * 16 + fr;
;                 const float* base = xp ? (row < MP ? xp + (size_t)row * D : xs + (size_t)(row - MP) * D) : X + (size_t)row * D;
;                 const float* gp = gate + (size_t)mod_row(row) * 6144;
; #pragma unroll
;                 for (int bj = 0; bj < 2; ++bj)
; #pragma unroll
;                     for (int n = 0; n < 2; ++n) { const int col = u.pn * 256 + bj * 128 + wc * 32 + n * 16 + fq * 4;
;                         const f32x4 ga = *(const f32x4*)(gp + col) * acc[ai][bj][m][n];
;                         if (u.split) { *(f32x4*)(part + ((size_t)(u.k0 >> 8) * MS + (row - MP)) * D + col) = ga;
;                         } else *(f32x4*)(X + (size_t)row * D + col) = *(const f32x4*)(base + col) + ga; } }
;     }
	v_pk_mul_f32 v[78:79], v[78:79], v[190:191]
	v_pk_mul_f32 v[76:77], v[76:77], v[188:189]
	v_pk_add_f32 v[78:79], v[78:79], v[210:211]
	v_pk_add_f32 v[76:77], v[76:77], v[208:209]
	v_pk_mul_f32 v[74:75], v[74:75], v[194:195]
	v_pk_mul_f32 v[72:73], v[72:73], v[192:193]
	v_pk_add_f32 v[74:75], v[74:75], v[214:215]
	v_pk_add_f32 v[72:73], v[72:73], v[212:213]
	v_pk_mul_f32 v[70:71], v[70:71], v[130:131]
	v_pk_mul_f32 v[68:69], v[68:69], v[128:129]
	v_pk_add_f32 v[70:71], v[70:71], v[218:219]
	v_pk_add_f32 v[68:69], v[68:69], v[216:217]
	v_pk_mul_f32 v[66:67], v[66:67], v[142:143]
	v_pk_mul_f32 v[64:65], v[64:65], v[140:141]
	v_pk_add_f32 v[66:67], v[66:67], v[222:223]
	v_pk_add_f32 v[64:65], v[64:65], v[220:221]
	global_store_dwordx4 v[146:147], v[76:79], off
	global_store_dwordx4 v[146:147], v[72:75], off offset:64
	global_store_dwordx4 v[146:147], v[68:71], off offset:512
	global_store_dwordx4 v[146:147], v[64:67], off offset:576
	v_lshl_add_u64 v[146:147], v[146:147], 0, s[98:99]
	global_load_dwordx4 v[208:211], v[144:145], off
	global_load_dwordx4 v[212:215], v[144:145], off offset:64
	global_load_dwordx4 v[216:219], v[144:145], off offset:512
	global_load_dwordx4 v[220:223], v[144:145], off offset:576
	v_lshl_add_u64 v[144:145], v[144:145], 0, s[66:67]
	s_waitcnt vmcnt(16)
	v_pk_mul_f32 v[62:63], v[62:63], v[190:191]
	v_pk_mul_f32 v[60:61], v[60:61], v[188:189]
	v_pk_add_f32 v[62:63], v[62:63], v[226:227]
	v_pk_add_f32 v[60:61], v[60:61], v[224:225]
	v_pk_mul_f32 v[58:59], v[58:59], v[194:195]
	v_pk_mul_f32 v[56:57], v[56:57], v[192:193]
	v_pk_add_f32 v[58:59], v[58:59], v[230:231]
	v_pk_add_f32 v[56:57], v[56:57], v[228:229]
	v_pk_mul_f32 v[54:55], v[54:55], v[130:131]
	v_pk_mul_f32 v[52:53], v[52:53], v[128:129]
	v_pk_add_f32 v[54:55], v[54:55], v[234:235]
	v_pk_add_f32 v[52:53], v[52:53], v[232:233]
	v_pk_mul_f32 v[50:51], v[50:51], v[142:143]
	v_pk_mul_f32 v[48:49], v[48:49], v[140:141]
	v_pk_add_f32 v[50:51], v[50:51], v[238:239]
	v_pk_add_f32 v[48:49], v[48:49], v[236:237]
	global_store_dwordx4 v[146:147], v[60:63], off
	global_store_dwordx4 v[146:147], v[56:59], off offset:64
	global_store_dwordx4 v[146:147], v[52:55], off offset:512
	global_store_dwordx4 v[146:147], v[48:51], off offset:576
	v_lshl_add_u64 v[146:147], v[146:147], 0, s[70:71]
	global_load_dwordx4 v[224:227], v[144:145], off
	global_load_dwordx4 v[228:231], v[144:145], off offset:64
	global_load_dwordx4 v[232:235], v[144:145], off offset:512
	global_load_dwordx4 v[236:239], v[144:145], off offset:576
	s_waitcnt vmcnt(16)
	v_pk_mul_f32 v[46:47], v[46:47], v[190:191]
	v_pk_mul_f32 v[44:45], v[44:45], v[188:189]
	v_pk_add_f32 v[46:47], v[46:47], v[242:243]
	v_pk_add_f32 v[44:45], v[44:45], v[240:241]
	v_pk_mul_f32 v[42:43], v[42:43], v[194:195]
	v_pk_mul_f32 v[40:41], v[40:41], v[192:193]
	v_pk_add_f32 v[42:43], v[42:43], v[246:247]
	v_pk_add_f32 v[40:41], v[40:41], v[244:245]
	v_pk_mul_f32 v[38:39], v[38:39], v[130:131]
	v_pk_mul_f32 v[36:37], v[36:37], v[128:129]
	v_pk_add_f32 v[38:39], v[38:39], v[250:251]
	v_pk_add_f32 v[36:37], v[36:37], v[248:249]
	v_pk_mul_f32 v[34:35], v[34:35], v[142:143]
	v_pk_mul_f32 v[32:33], v[32:33], v[140:141]
	v_pk_add_f32 v[34:35], v[34:35], v[186:187]
	v_pk_add_f32 v[32:33], v[32:33], v[184:185]
	global_store_dwordx4 v[146:147], v[44:47], off
	global_store_dwordx4 v[146:147], v[40:43], off offset:64
	global_store_dwordx4 v[146:147], v[36:39], off offset:512
	global_store_dwordx4 v[146:147], v[32:35], off offset:576
	v_lshl_add_u64 v[146:147], v[146:147], 0, s[70:71]
	s_waitcnt vmcnt(12)
	v_pk_mul_f32 v[30:31], v[30:31], v[190:191]
	v_pk_mul_f32 v[28:29], v[28:29], v[188:189]
	v_pk_add_f32 v[30:31], v[30:31], v[210:211]
	v_pk_add_f32 v[28:29], v[28:29], v[208:209]
	v_pk_mul_f32 v[26:27], v[26:27], v[194:195]
	v_pk_mul_f32 v[24:25], v[24:25], v[192:193]
	v_pk_add_f32 v[26:27], v[26:27], v[214:215]
	v_pk_add_f32 v[24:25], v[24:25], v[212:213]
	v_pk_mul_f32 v[22:23], v[22:23], v[130:131]
	v_pk_mul_f32 v[20:21], v[20:21], v[128:129]
	v_pk_add_f32 v[22:23], v[22:23], v[218:219]
	v_pk_add_f32 v[20:21], v[20:21], v[216:217]
	v_pk_mul_f32 v[18:19], v[18:19], v[142:143]
	v_pk_mul_f32 v[16:17], v[16:17], v[140:141]
	v_pk_add_f32 v[18:19], v[18:19], v[222:223]
	v_pk_add_f32 v[16:17], v[16:17], v[220:221]
	global_store_dwordx4 v[146:147], v[28:31], off
	global_store_dwordx4 v[146:147], v[24:27], off offset:64
	global_store_dwordx4 v[146:147], v[20:23], off offset:512
	global_store_dwordx4 v[146:147], v[16:19], off offset:576
	v_lshl_add_u64 v[146:147], v[146:147], 0, s[70:71]
	s_waitcnt vmcnt(8)
	v_pk_mul_f32 v[14:15], v[14:15], v[190:191]
	v_pk_mul_f32 v[12:13], v[12:13], v[188:189]
	v_pk_add_f32 v[14:15], v[14:15], v[226:227]
	v_pk_add_f32 v[12:13], v[12:13], v[224:225]
	v_pk_mul_f32 v[10:11], v[10:11], v[194:195]
	v_pk_mul_f32 v[8:9], v[8:9], v[192:193]
	v_pk_add_f32 v[10:11], v[10:11], v[230:231]
	v_pk_add_f32 v[8:9], v[8:9], v[228:229]
	v_pk_mul_f32 v[6:7], v[6:7], v[130:131]
	v_pk_mul_f32 v[4:5], v[4:5], v[128:129]
	v_pk_add_f32 v[6:7], v[6:7], v[234:235]
	v_pk_add_f32 v[4:5], v[4:5], v[232:233]
	v_pk_mul_f32 v[2:3], v[2:3], v[142:143]
	v_pk_mul_f32 v[0:1], v[0:1], v[140:141]
	v_pk_add_f32 v[2:3], v[2:3], v[238:239]
	v_pk_add_f32 v[0:1], v[0:1], v[236:237]
	global_store_dwordx4 v[146:147], v[12:15], off
	global_store_dwordx4 v[146:147], v[8:11], off offset:64
	global_store_dwordx4 v[146:147], v[4:7], off offset:512
	global_store_dwordx4 v[146:147], v[0:3], off offset:576
	s_branch .Lepi_out_done
;     __device__ __forceinline__ void operator()(const Acc& acc, const Unit& u, int wr, int wc, int fr, int fq) const {
; #pragma unroll
;         for (int ai = 0; ai < 2; ++ai)
; #pragma unroll
;             for (int m = 0; m < 4; ++m) { const int row = u.pm * 256 + ai * 128 + wr * 64 + m * 16 + fr;
;                 const float* base = xp ? (row < MP ? xp + (size_t)row * D : xs + (size_t)(row - MP) * D) : X + (size_t)row * D;
;                 const float* gp = gate + (size_t)mod_row(row) * 6144;
; #pragma unroll
;                 for (int bj = 0; bj < 2; ++bj)
; #pragma unroll
;                     for (int n = 0; n < 2; ++n) { const int col = u.pn * 256 + bj * 128 + wc * 32 + n * 16 + fq * 4;
;                         const f32x4 ga = *(const f32x4*)(gp + col) * acc[ai][bj][m][n];
;                         if (u.split) { *(f32x4*)(part + ((size_t)(u.k0 >> 8) * MS + (row - MP)) * D + col) = ga;
;                         } else *(f32x4*)(X + (size_t)row * D + col) = *(const f32x4*)(base + col) + ga; } }
;     }
.Lepi_out_split:
	s_mov_b32 s66, 0x18000
	s_mov_b32 s67, 0
	s_mov_b32 s68, 0x78000
	s_mov_b32 s69, 0
	v_add_u32_e32 v207, 0xffffc000, v207
	s_lshr_b32 s2, s12, 8
	s_lshl_b32 s2, s2, 21
	s_add_u32 s2, s53, s2
	s_addc_u32 s3, s54, 0
	v_lshlrev_b32_e32 v159, 2, v159
	v_lshl_add_u32 v196, v207, 12, v159
	v_lshl_add_u64 v[146:147], v[196:197], 0, s[2:3]
	v_lshrrev_b32_e32 v207, 2, v207
	v_add_u32_e32 v207, 4, v207
	v_mad_u32_u24 v196, v207, s80, v159
	v_lshl_add_u64 v[144:145], v[196:197], 0, s[18:19]
	global_load_dwordx4 v[208:211], v[144:145], off
	global_load_dwordx4 v[212:215], v[144:145], off offset:64
	global_load_dwordx4 v[216:219], v[144:145], off offset:512
	global_load_dwordx4 v[220:223], v[144:145], off offset:576
	v_lshl_add_u64 v[144:145], v[144:145], 0, s[66:67]
	global_load_dwordx4 v[224:227], v[144:145], off
	global_load_dwordx4 v[228:231], v[144:145], off offset:64
	global_load_dwordx4 v[232:235], v[144:145], off offset:512
	global_load_dwordx4 v[236:239], v[144:145], off offset:576
	v_lshl_add_u64 v[144:145], v[144:145], 0, s[66:67]
	global_load_dwordx4 v[240:243], v[144:145], off
	global_load_dwordx4 v[244:247], v[144:145], off offset:64
	global_load_dwordx4 v[248:251], v[144:145], off offset:512
	global_load_dwordx4 v[184:187], v[144:145], off offset:576
	v_lshl_add_u64 v[144:145], v[144:145], 0, s[66:67]
	s_waitcnt vmcnt(8)
	v_pk_mul_f32 v[126:127], v[126:127], v[210:211]
	v_pk_mul_f32 v[124:125], v[124:125], v[208:209]
	v_pk_mul_f32 v[122:123], v[122:123], v[214:215]
	v_pk_mul_f32 v[120:121], v[120:121], v[212:213]
	v_pk_mul_f32 v[118:119], v[118:119], v[218:219]
	v_pk_mul_f32 v[116:117], v[116:117], v[216:217]
	v_pk_mul_f32 v[114:115], v[114:115], v[222:223]
	v_pk_mul_f32 v[112:113], v[112:113], v[220:221]
	global_store_dwordx4 v[146:147], v[124:127], off
	global_store_dwordx4 v[146:147], v[120:123], off offset:64
	global_store_dwordx4 v[146:147], v[116:119], off offset:512
	global_store_dwordx4 v[146:147], v[112:115], off offset:576
	v_lshl_add_u64 v[146:147], v[146:147], 0, s[70:71]
	global_load_dwordx4 v[208:211], v[144:145], off
	global_load_dwordx4 v[212:215], v[144:145], off offset:64
	global_load_dwordx4 v[216:219], v[144:145], off offset:512
	global_load_dwordx4 v[220:223], v[144:145], off offset:576
	v_lshl_add_u64 v[144:145], v[144:145], 0, s[68:69]
	s_waitcnt vmcnt(12)
	v_pk_mul_f32 v[110:111], v[110:111], v[226:227]
	v_pk_mul_f32 v[108:109], v[108:109], v[224:225]
	v_pk_mul_f32 v[106:107], v[106:107], v[230:231]
	v_pk_mul_f32 v[104:105], v[104:105], v[228:229]
	v_pk_mul_f32 v[102:103], v[102:103], v[234:235]
	v_pk_mul_f32 v[100:101], v[100:101], v[232:233]
	v_pk_mul_f32 v[98:99], v[98:99], v[238:239]
	v_pk_mul_f32 v[96:97], v[96:97], v[236:237]
	global_store_dwordx4 v[146:147], v[108:111], off
	global_store_dwordx4 v[146:147], v[104:107], off offset:64
	global_store_dwordx4 v[146:147], v[100:103], off offset:512
	global_store_dwordx4 v[146:147], v[96:99], off offset:576
	v_lshl_add_u64 v[146:147], v[146:147], 0, s[70:71]
	global_load_dwordx4 v[224:227], v[144:145], off
	global_load_dwordx4 v[228:231], v[144:145], off offset:64
	global_load_dwordx4 v[232:235], v[144:145], off offset:512
	global_load_dwordx4 v[236:239], v[144:145], off offset:576
	v_lshl_add_u64 v[144:145], v[144:145], 0, s[66:67]
	s_waitcnt vmcnt(16)
	v_pk_mul_f32 v[94:95], v[94:95], v[242:243]
	v_pk_mul_f32 v[92:93], v[92:93], v[240:241]
	v_pk_mul_f32 v[90:91], v[90:91], v[246:247]
	v_pk_mul_f32 v[88:89], v[88:89], v[244:245]
	v_pk_mul_f32 v[86:87], v[86:87], v[250:251]
	v_pk_mul_f32 v[84:85], v[84:85], v[248:249]
	v_pk_mul_f32 v[82:83], v[82:83], v[186:187]
	v_pk_mul_f32 v[80:81], v[80:81], v[184:185]
	global_store_dwordx4 v[146:147], v[92:95], off
	global_store_dwordx4 v[146:147], v[88:91], off offset:64
	global_store_dwordx4 v[146:147], v[84:87], off offset:512
	global_store_dwordx4 v[146:147], v[80:83], off offset:576
	v_lshl_add_u64 v[146:147], v[146:147], 0, s[70:71]
	global_load_dwordx4 v[240:243], v[144:145], off
	global_load_dwordx4 v[244:247], v[144:145], off offset:64
	global_load_dwordx4 v[248:251], v[144:145], off offset:512
	global_load_dwordx4 v[184:187], v[144:145], off offset:576
	v_lshl_add_u64 v[144:145], v[144:145], 0, s[66:67]
	s_waitcnt vmcnt(16)
;     __device__ __forceinline__ void operator()(const Acc& acc, const Unit& u, int wr, int wc, int fr, int fq) const {
; #pragma unroll
;         for (int ai = 0; ai < 2; ++ai)
; #pragma unroll
;             for (int m = 0; m < 4; ++m) { const int row = u.pm * 256 + ai * 128 + wr * 64 + m * 16 + fr;
;                 const float* base = xp ? (row < MP ? xp + (size_t)row * D : xs + (size_t)(row - MP) * D) : X + (size_t)row * D;
;                 const float* gp = gate + (size_t)mod_row(row) * 6144;
; #pragma unroll
;                 for (int bj = 0; bj < 2; ++bj)
; #pragma unroll
;                     for (int n = 0; n < 2; ++n) { const int col = u.pn * 256 + bj * 128 + wc * 32 + n * 16 + fq * 4;
;                         const f32x4 ga = *(const f32x4*)(gp + col) * acc[ai][bj][m][n];
;                         if (u.split) { *(f32x4*)(part + ((size_t)(u.k0 >> 8) * MS + (row - MP)) * D + col) = ga;
;                         } else *(f32x4*)(X + (size_t)row * D + col) = *(const f32x4*)(base + col) + ga; } }
;     }
	v_pk_mul_f32 v[78:79], v[78:79], v[210:211]
	v_pk_mul_f32 v[76:77], v[76:77], v[208:209]
	v_pk_mul_f32 v[74:75], v[74:75], v[214:215]
	v_pk_mul_f32 v[72:73], v[72:73], v[212:213]
	v_pk_mul_f32 v[70:71], v[70:71], v[218:219]
	v_pk_mul_f32 v[68:69], v[68:69], v[216:217]
	v_pk_mul_f32 v[66:67], v[66:67], v[222:223]
	v_pk_mul_f32 v[64:65], v[64:65], v[220:221]
	global_store_dwordx4 v[146:147], v[76:79], off
	global_store_dwordx4 v[146:147], v[72:75], off offset:64
	global_store_dwordx4 v[146:147], v[68:71], off offset:512
	global_store_dwordx4 v[146:147], v[64:67], off offset:576
	v_lshl_add_u64 v[146:147], v[146:147], 0, s[98:99]
	global_load_dwordx4 v[208:211], v[144:145], off
	global_load_dwordx4 v[212:215], v[144:145], off offset:64
	global_load_dwordx4 v[216:219], v[144:145], off offset:512
	global_load_dwordx4 v[220:223], v[144:145], off offset:576
	v_lshl_add_u64 v[144:145], v[144:145], 0, s[66:67]
	s_waitcnt vmcnt(16)
	v_pk_mul_f32 v[62:63], v[62:63], v[226:227]
	v_pk_mul_f32 v[60:61], v[60:61], v[224:225]
	v_pk_mul_f32 v[58:59], v[58:59], v[230:231]
	v_pk_mul_f32 v[56:57], v[56:57], v[228:229]
	v_pk_mul_f32 v[54:55], v[54:55], v[234:235]
	v_pk_mul_f32 v[52:53], v[52:53], v[232:233]
	v_pk_mul_f32 v[50:51], v[50:51], v[238:239]
	v_pk_mul_f32 v[48:49], v[48:49], v[236:237]
	global_store_dwordx4 v[146:147], v[60:63], off
	global_store_dwordx4 v[146:147], v[56:59], off offset:64
	global_store_dwordx4 v[146:147], v[52:55], off offset:512
	global_store_dwordx4 v[146:147], v[48:51], off offset:576
	v_lshl_add_u64 v[146:147], v[146:147], 0, s[70:71]
	global_load_dwordx4 v[224:227], v[144:145], off
	global_load_dwordx4 v[228:231], v[144:145], off offset:64
	global_load_dwordx4 v[232:235], v[144:145], off offset:512
	global_load_dwordx4 v[236:239], v[144:145], off offset:576
	s_waitcnt vmcnt(16)
	v_pk_mul_f32 v[46:47], v[46:47], v[242:243]
	v_pk_mul_f32 v[44:45], v[44:45], v[240:241]
	v_pk_mul_f32 v[42:43], v[42:43], v[246:247]
	v_pk_mul_f32 v[40:41], v[40:41], v[244:245]
	v_pk_mul_f32 v[38:39], v[38:39], v[250:251]
	v_pk_mul_f32 v[36:37], v[36:37], v[248:249]
	v_pk_mul_f32 v[34:35], v[34:35], v[186:187]
	v_pk_mul_f32 v[32:33], v[32:33], v[184:185]
	global_store_dwordx4 v[146:147], v[44:47], off
	global_store_dwordx4 v[146:147], v[40:43], off offset:64
	global_store_dwordx4 v[146:147], v[36:39], off offset:512
	global_store_dwordx4 v[146:147], v[32:35], off offset:576
	v_lshl_add_u64 v[146:147], v[146:147], 0, s[70:71]
	s_waitcnt vmcnt(12)
	v_pk_mul_f32 v[30:31], v[30:31], v[210:211]
	v_pk_mul_f32 v[28:29], v[28:29], v[208:209]
	v_pk_mul_f32 v[26:27], v[26:27], v[214:215]
	v_pk_mul_f32 v[24:25], v[24:25], v[212:213]
	v_pk_mul_f32 v[22:23], v[22:23], v[218:219]
	v_pk_mul_f32 v[20:21], v[20:21], v[216:217]
	v_pk_mul_f32 v[18:19], v[18:19], v[222:223]
	v_pk_mul_f32 v[16:17], v[16:17], v[220:221]
	global_store_dwordx4 v[146:147], v[28:31], off
	global_store_dwordx4 v[146:147], v[24:27], off offset:64
	global_store_dwordx4 v[146:147], v[20:23], off offset:512
	global_store_dwordx4 v[146:147], v[16:19], off offset:576
	v_lshl_add_u64 v[146:147], v[146:147], 0, s[70:71]
	s_waitcnt vmcnt(8)
	v_pk_mul_f32 v[14:15], v[14:15], v[226:227]
	v_pk_mul_f32 v[12:13], v[12:13], v[224:225]
	v_pk_mul_f32 v[10:11], v[10:11], v[230:231]
	v_pk_mul_f32 v[8:9], v[8:9], v[228:229]
	v_pk_mul_f32 v[6:7], v[6:7], v[234:235]
	v_pk_mul_f32 v[4:5], v[4:5], v[232:233]
	v_pk_mul_f32 v[2:3], v[2:3], v[238:239]
	v_pk_mul_f32 v[0:1], v[0:1], v[236:237]
	global_store_dwordx4 v[146:147], v[12:15], off
	global_store_dwordx4 v[146:147], v[8:11], off offset:64
	global_store_dwordx4 v[146:147], v[4:7], off offset:512
	global_store_dwordx4 v[146:147], v[0:3], off offset:576
.Lepi_out_done:
	s_and_b64 vcc, exec, s[0:1]
	s_mov_b64 s[0:1], -1
	s_cbranch_vccnz .LBB0_1421
	s_andn2_b64 vcc, exec, s[14:15]
	s_cbranch_vccnz .LBB0_1420
	s_barrier
	s_branch .LBB0_1420

;     __device__ __forceinline__ void operator()(const Acc& acc, const Unit& u, int wr, int wc, int fr, int fq) const {
; #pragma unroll
;         for (int ai = 0; ai < 2; ++ai)
; #pragma unroll
;             for (int m = 0; m < 4; ++m) { const int row = u.pm * 256 + ai * 128 + wr * 64 + m * 16 + fr;
;                 const float* base = xp ? (row < MP ? xp + (size_t)row * D : xs + (size_t)(row - MP) * D) : X + (size_t)row * D;
;                 const float* gp = gate + (size_t)mod_row(row) * 6144;
; #pragma unroll
;                 for (int bj = 0; bj < 2; ++bj)
; #pragma unroll
;                     for (int n = 0; n < 2; ++n) { const int col = u.pn * 256 + bj * 128 + wc * 32 + n * 16 + fq * 4;
;                         const f32x4 ga = *(const f32x4*)(gp + col) * acc[ai][bj][m][n];
;                         if (u.split) { *(f32x4*)(part + ((size_t)(u.k0 >> 8) * MS + (row - MP)) * D + col) = ga;
;                         } else *(f32x4*)(X + (size_t)row * D + col) = *(const f32x4*)(base + col) + ga; } }
;     }
.LBB0_1882:
	s_lshl_b32 s2, s55, 8
	s_add_i32 s2, s2, s43
	s_lshl_b32 s3, s53, 8
	s_add_i32 s3, s3, s44
	v_add_u32_e32 v207, s2, v151
	v_lshl_add_u32 v159, v152, 2, s3
	v_mov_b32_e32 v197, 0
	s_mov_b32 s70, 0x10000
	s_mov_b32 s71, 0
	s_mov_b32 s98, 0x50000
	s_mov_b32 s99, 0
	s_cmp_lg_u32 s54, 0
	s_cbranch_scc1 .Lepi_dn_split
	s_mov_b32 s66, 0x10000
	s_mov_b32 s67, 0
	s_mov_b32 s68, 0x50000
	s_mov_b32 s69, 0
	v_lshlrev_b32_e32 v196, 12, v207
	v_lshl_add_u32 v196, v159, 2, v196
	v_lshrrev_b32_e32 v207, 12, v207
	v_lshlrev_b32_e32 v159, 2, v159
	v_mad_u32_u24 v144, v207, s80, v159
	v_mov_b32_e32 v145, 0
	v_lshl_add_u64 v[144:145], v[144:145], 0, s[12:13]
	global_load_dwordx4 v[188:191], v[144:145], off
	global_load_dwordx4 v[192:195], v[144:145], off offset:64
	global_load_dwordx4 v[128:131], v[144:145], off offset:512
	global_load_dwordx4 v[140:143], v[144:145], off offset:576
	v_lshl_add_u64 v[146:147], v[196:197], 0, s[10:11]
	v_lshl_add_u64 v[144:145], v[196:197], 0, s[10:11]
	global_load_dwordx4 v[208:211], v[144:145], off
	global_load_dwordx4 v[212:215], v[144:145], off offset:64
	global_load_dwordx4 v[216:219], v[144:145], off offset:512
	global_load_dwordx4 v[220:223], v[144:145], off offset:576
	v_lshl_add_u64 v[144:145], v[144:145], 0, s[66:67]
	global_load_dwordx4 v[224:227], v[144:145], off
	global_load_dwordx4 v[228:231], v[144:145], off offset:64
	global_load_dwordx4 v[232:235], v[144:145], off offset:512
	global_load_dwordx4 v[236:239], v[144:145], off offset:576
	v_lshl_add_u64 v[144:145], v[144:145], 0, s[66:67]
	global_load_dwordx4 v[240:243], v[144:145], off
	global_load_dwordx4 v[244:247], v[144:145], off offset:64
	global_load_dwordx4 v[248:251], v[144:145], off offset:512
	global_load_dwordx4 v[184:187], v[144:145], off offset:576
	v_lshl_add_u64 v[144:145], v[144:145], 0, s[66:67]
	s_waitcnt vmcnt(8)
	v_pk_mul_f32 v[126:127], v[126:127], v[190:191]
	v_pk_mul_f32 v[124:125], v[124:125], v[188:189]
	v_pk_add_f32 v[126:127], v[126:127], v[210:211]
	v_pk_add_f32 v[124:125], v[124:125], v[208:209]
	v_pk_mul_f32 v[122:123], v[122:123], v[194:195]
	v_pk_mul_f32 v[120:121], v[120:121], v[192:193]
	v_pk_add_f32 v[122:123], v[122:123], v[214:215]
	v_pk_add_f32 v[120:121], v[120:121], v[212:213]
	v_pk_mul_f32 v[118:119], v[118:119], v[130:131]
	v_pk_mul_f32 v[116:117], v[116:117], v[128:129]
	v_pk_add_f32 v[118:119], v[118:119], v[218:219]
	v_pk_add_f32 v[116:117], v[116:117], v[216:217]
	v_pk_mul_f32 v[114:115], v[114:115], v[142:143]
	v_pk_mul_f32 v[112:113], v[112:113], v[140:141]
	v_pk_add_f32 v[114:115], v[114:115], v[222:223]
	v_pk_add_f32 v[112:113], v[112:113], v[220:221]
	global_store_dwordx4 v[146:147], v[124:127], off
	global_store_dwordx4 v[146:147], v[120:123], off offset:64
	global_store_dwordx4 v[146:147], v[116:119], off offset:512
	global_store_dwordx4 v[146:147], v[112:115], off offset:576
	v_lshl_add_u64 v[146:147], v[146:147], 0, s[70:71]
	global_load_dwordx4 v[208:211], v[144:145], off
	global_load_dwordx4 v[212:215], v[144:145], off offset:64
	global_load_dwordx4 v[216:219], v[144:145], off offset:512
	global_load_dwordx4 v[220:223], v[144:145], off offset:576
	v_lshl_add_u64 v[144:145], v[144:145], 0, s[68:69]
	s_waitcnt vmcnt(12)
	v_pk_mul_f32 v[110:111], v[110:111], v[190:191]
	v_pk_mul_f32 v[108:109], v[108:109], v[188:189]
	v_pk_add_f32 v[110:111], v[110:111], v[226:227]
	v_pk_add_f32 v[108:109], v[108:109], v[224:225]
	v_pk_mul_f32 v[106:107], v[106:107], v[194:195]
	v_pk_mul_f32 v[104:105], v[104:105], v[192:193]
	v_pk_add_f32 v[106:107], v[106:107], v[230:231]
	v_pk_add_f32 v[104:105], v[104:105], v[228:229]
	v_pk_mul_f32 v[102:103], v[102:103], v[130:131]
	v_pk_mul_f32 v[100:101], v[100:101], v[128:129]
	v_pk_add_f32 v[102:103], v[102:103], v[234:235]
	v_pk_add_f32 v[100:101], v[100:101], v[232:233]
	v_pk_mul_f32 v[98:99], v[98:99], v[142:143]
	v_pk_mul_f32 v[96:97], v[96:97], v[140:141]
	v_pk_add_f32 v[98:99], v[98:99], v[238:239]
	v_pk_add_f32 v[96:97], v[96:97], v[236:237]
	global_store_dwordx4 v[146:147], v[108:111], off
	global_store_dwordx4 v[146:147], v[104:107], off offset:64
	global_store_dwordx4 v[146:147], v[100:103], off offset:512
	global_store_dwordx4 v[146:147], v[96:99], off offset:576
	v_lshl_add_u64 v[146:147], v[146:147], 0, s[70:71]
	global_load_dwordx4 v[224:227], v[144:145], off
	global_load_dwordx4 v[228:231], v[144:145], off offset:64
	global_load_dwordx4 v[232:235], v[144:145], off offset:512
	global_load_dwordx4 v[236:239], v[144:145], off offset:576
	v_lshl_add_u64 v[144:145], v[144:145], 0, s[66:67]
	s_waitcnt vmcnt(16)
	v_pk_mul_f32 v[94:95], v[94:95], v[190:191]
	v_pk_mul_f32 v[92:93], v[92:93], v[188:189]
	v_pk_add_f32 v[94:95], v[94:95], v[242:243]
	v_pk_add_f32 v[92:93], v[92:93], v[240:241]
	v_pk_mul_f32 v[90:91], v[90:91], v[194:195]
	v_pk_mul_f32 v[88:89], v[88:89], v[192:193]
	v_pk_add_f32 v[90:91], v[90:91], v[246:247]
	v_pk_add_f32 v[88:89], v[88:89], v[244:245]
	v_pk_mul_f32 v[86:87], v[86:87], v[130:131]
	v_pk_mul_f32 v[84:85], v[84:85], v[128:129]
	v_pk_add_f32 v[86:87], v[86:87], v[250:251]
	v_pk_add_f32 v[84:85], v[84:85], v[248:249]
	v_pk_mul_f32 v[82:83], v[82:83], v[142:143]
	v_pk_mul_f32 v[80:81], v[80:81], v[140:141]
	v_pk_add_f32 v[82:83], v[82:83], v[186:187]
	v_pk_add_f32 v[80:81], v[80:81], v[184:185]
	global_store_dwordx4 v[146:147], v[92:95], off
	global_store_dwordx4 v[146:147], v[88:91], off offset:64
	global_store_dwordx4 v[146:147], v[84:87], off offset:512
	global_store_dwordx4 v[146:147], v[80:83], off offset:576
	v_lshl_add_u64 v[146:147], v[146:147], 0, s[70:71]
	global_load_dwordx4 v[240:243], v[144:145], off
	global_load_dwordx4 v[244:247], v[144:145], off offset:64
	global_load_dwordx4 v[248:251], v[144:145], off offset:512
	global_load_dwordx4 v[184:187], v[144:145], off offset:576
	v_lshl_add_u64 v[144:145], v[144:145], 0, s[66:67]
	s_waitcnt vmcnt(16)
;     __device__ __forceinline__ void operator()(const Acc& acc, const Unit& u, int wr, int wc, int fr, int fq) const {
; #pragma unroll
;         for (int ai = 0; ai < 2; ++ai)
; #pragma unroll
;             for (int m = 0; m < 4; ++m) { const int row = u.pm * 256 + ai * 128 + wr * 64 + m * 16 + fr;
;                 const float* base = xp ? (row < MP ? xp + (size_t)row * D : xs + (size_t)(row - MP) * D) : X + (size_t)row * D;
;                 const float* gp = gate + (size_t)mod_row(row) * 6144;
; #pragma unroll
;                 for (int bj = 0; bj < 2; ++bj)
; #pragma unroll
;                     for (int n = 0; n < 2; ++n) { const int col = u.pn * 256 + bj * 128 + wc * 32 + n * 16 + fq * 4;
;                         const f32x4 ga = *(const f32x4*)(gp + col) * acc[ai][bj][m][n];
;                         if (u.split) { *(f32x4*)(part + ((size_t)(u.k0 >> 8) * MS + (row - MP)) * D + col) = ga;
;                         } else *(f32x4*)(X + (size_t)row * D + col) = *(const f32x4*)(base + col) + ga; } }
;     }
	v_pk_mul_f32 v[78:79], v[78:79], v[190:191]
	v_pk_mul_f32 v[76:77], v[76:77], v[188:189]
	v_pk_add_f32 v[78:79], v[78:79], v[210:211]
	v_pk_add_f32 v[76:77], v[76:77], v[208:209]
	v_pk_mul_f32 v[74:75], v[74:75], v[194:195]
	v_pk_mul_f32 v[72:73], v[72:73], v[192:193]
	v_pk_add_f32 v[74:75], v[74:75], v[214:215]
	v_pk_add_f32 v[72:73], v[72:73], v[212:213]
	v_pk_mul_f32 v[70:71], v[70:71], v[130:131]
	v_pk_mul_f32 v[68:69], v[68:69], v[128:129]
	v_pk_add_f32 v[70:71], v[70:71], v[218:219]
	v_pk_add_f32 v[68:69], v[68:69], v[216:217]
	v_pk_mul_f32 v[66:67], v[66:67], v[142:143]
	v_pk_mul_f32 v[64:65], v[64:65], v[140:141]
	v_pk_add_f32 v[66:67], v[66:67], v[222:223]
	v_pk_add_f32 v[64:65], v[64:65], v[220:221]
	global_store_dwordx4 v[146:147], v[76:79], off
	global_store_dwordx4 v[146:147], v[72:75], off offset:64
	global_store_dwordx4 v[146:147], v[68:71], off offset:512
	global_store_dwordx4 v[146:147], v[64:67], off offset:576
	v_lshl_add_u64 v[146:147], v[146:147], 0, s[98:99]
	global_load_dwordx4 v[208:211], v[144:145], off
	global_load_dwordx4 v[212:215], v[144:145], off offset:64
	global_load_dwordx4 v[216:219], v[144:145], off offset:512
	global_load_dwordx4 v[220:223], v[144:145], off offset:576
	v_lshl_add_u64 v[144:145], v[144:145], 0, s[66:67]
	s_waitcnt vmcnt(16)
	v_pk_mul_f32 v[62:63], v[62:63], v[190:191]
	v_pk_mul_f32 v[60:61], v[60:61], v[188:189]
	v_pk_add_f32 v[62:63], v[62:63], v[226:227]
	v_pk_add_f32 v[60:61], v[60:61], v[224:225]
	v_pk_mul_f32 v[58:59], v[58:59], v[194:195]
	v_pk_mul_f32 v[56:57], v[56:57], v[192:193]
	v_pk_add_f32 v[58:59], v[58:59], v[230:231]
	v_pk_add_f32 v[56:57], v[56:57], v[228:229]
	v_pk_mul_f32 v[54:55], v[54:55], v[130:131]
	v_pk_mul_f32 v[52:53], v[52:53], v[128:129]
	v_pk_add_f32 v[54:55], v[54:55], v[234:235]
	v_pk_add_f32 v[52:53], v[52:53], v[232:233]
	v_pk_mul_f32 v[50:51], v[50:51], v[142:143]
	v_pk_mul_f32 v[48:49], v[48:49], v[140:141]
	v_pk_add_f32 v[50:51], v[50:51], v[238:239]
	v_pk_add_f32 v[48:49], v[48:49], v[236:237]
	global_store_dwordx4 v[146:147], v[60:63], off
	global_store_dwordx4 v[146:147], v[56:59], off offset:64
	global_store_dwordx4 v[146:147], v[52:55], off offset:512
	global_store_dwordx4 v[146:147], v[48:51], off offset:576
	v_lshl_add_u64 v[146:147], v[146:147], 0, s[70:71]
	global_load_dwordx4 v[224:227], v[144:145], off
	global_load_dwordx4 v[228:231], v[144:145], off offset:64
	global_load_dwordx4 v[232:235], v[144:145], off offset:512
	global_load_dwordx4 v[236:239], v[144:145], off offset:576
	s_waitcnt vmcnt(16)
	v_pk_mul_f32 v[46:47], v[46:47], v[190:191]
	v_pk_mul_f32 v[44:45], v[44:45], v[188:189]
	v_pk_add_f32 v[46:47], v[46:47], v[242:243]
	v_pk_add_f32 v[44:45], v[44:45], v[240:241]
	v_pk_mul_f32 v[42:43], v[42:43], v[194:195]
	v_pk_mul_f32 v[40:41], v[40:41], v[192:193]
	v_pk_add_f32 v[42:43], v[42:43], v[246:247]
	v_pk_add_f32 v[40:41], v[40:41], v[244:245]
	v_pk_mul_f32 v[38:39], v[38:39], v[130:131]
	v_pk_mul_f32 v[36:37], v[36:37], v[128:129]
	v_pk_add_f32 v[38:39], v[38:39], v[250:251]
	v_pk_add_f32 v[36:37], v[36:37], v[248:249]
	v_pk_mul_f32 v[34:35], v[34:35], v[142:143]
	v_pk_mul_f32 v[32:33], v[32:33], v[140:141]
	v_pk_add_f32 v[34:35], v[34:35], v[186:187]
	v_pk_add_f32 v[32:33], v[32:33], v[184:185]
	global_store_dwordx4 v[146:147], v[44:47], off
	global_store_dwordx4 v[146:147], v[40:43], off offset:64
	global_store_dwordx4 v[146:147], v[36:39], off offset:512
	global_store_dwordx4 v[146:147], v[32:35], off offset:576
	v_lshl_add_u64 v[146:147], v[146:147], 0, s[70:71]
	s_waitcnt vmcnt(12)
	v_pk_mul_f32 v[30:31], v[30:31], v[190:191]
	v_pk_mul_f32 v[28:29], v[28:29], v[188:189]
	v_pk_add_f32 v[30:31], v[30:31], v[210:211]
	v_pk_add_f32 v[28:29], v[28:29], v[208:209]
	v_pk_mul_f32 v[26:27], v[26:27], v[194:195]
	v_pk_mul_f32 v[24:25], v[24:25], v[192:193]
	v_pk_add_f32 v[26:27], v[26:27], v[214:215]
	v_pk_add_f32 v[24:25], v[24:25], v[212:213]
	v_pk_mul_f32 v[22:23], v[22:23], v[130:131]
	v_pk_mul_f32 v[20:21], v[20:21], v[128:129]
	v_pk_add_f32 v[22:23], v[22:23], v[218:219]
	v_pk_add_f32 v[20:21], v[20:21], v[216:217]
	v_pk_mul_f32 v[18:19], v[18:19], v[142:143]
	v_pk_mul_f32 v[16:17], v[16:17], v[140:141]
	v_pk_add_f32 v[18:19], v[18:19], v[222:223]
	v_pk_add_f32 v[16:17], v[16:17], v[220:221]
	global_store_dwordx4 v[146:147], v[28:31], off
	global_store_dwordx4 v[146:147], v[24:27], off offset:64
	global_store_dwordx4 v[146:147], v[20:23], off offset:512
	global_store_dwordx4 v[146:147], v[16:19], off offset:576
	v_lshl_add_u64 v[146:147], v[146:147], 0, s[70:71]
	s_waitcnt vmcnt(8)
	v_pk_mul_f32 v[14:15], v[14:15], v[190:191]
	v_pk_mul_f32 v[12:13], v[12:13], v[188:189]
	v_pk_add_f32 v[14:15], v[14:15], v[226:227]
	v_pk_add_f32 v[12:13], v[12:13], v[224:225]
	v_pk_mul_f32 v[10:11], v[10:11], v[194:195]
	v_pk_mul_f32 v[8:9], v[8:9], v[192:193]
	v_pk_add_f32 v[10:11], v[10:11], v[230:231]
	v_pk_add_f32 v[8:9], v[8:9], v[228:229]
	v_pk_mul_f32 v[6:7], v[6:7], v[130:131]
	v_pk_mul_f32 v[4:5], v[4:5], v[128:129]
	v_pk_add_f32 v[6:7], v[6:7], v[234:235]
	v_pk_add_f32 v[4:5], v[4:5], v[232:233]
	v_pk_mul_f32 v[2:3], v[2:3], v[142:143]
	v_pk_mul_f32 v[0:1], v[0:1], v[140:141]
	v_pk_add_f32 v[2:3], v[2:3], v[238:239]
	v_pk_add_f32 v[0:1], v[0:1], v[236:237]
	global_store_dwordx4 v[146:147], v[12:15], off
	global_store_dwordx4 v[146:147], v[8:11], off offset:64
	global_store_dwordx4 v[146:147], v[4:7], off offset:512
	global_store_dwordx4 v[146:147], v[0:3], off offset:576
	s_branch .Lepi_dn_done
;     __device__ __forceinline__ void operator()(const Acc& acc, const Unit& u, int wr, int wc, int fr, int fq) const {
; #pragma unroll
;         for (int ai = 0; ai < 2; ++ai)
; #pragma unroll
;             for (int m = 0; m < 4; ++m) { const int row = u.pm * 256 + ai * 128 + wr * 64 + m * 16 + fr;
;                 const float* base = xp ? (row < MP ? xp + (size_t)row * D : xs + (size_t)(row - MP) * D) : X + (size_t)row * D;
;                 const float* gp = gate + (size_t)mod_row(row) * 6144;
; #pragma unroll
;                 for (int bj = 0; bj < 2; ++bj)
; #pragma unroll
;                     for (int n = 0; n < 2; ++n) { const int col = u.pn * 256 + bj * 128 + wc * 32 + n * 16 + fq * 4;
;                         const f32x4 ga = *(const f32x4*)(gp + col) * acc[ai][bj][m][n];
;                         if (u.split) { *(f32x4*)(part + ((size_t)(u.k0 >> 8) * MS + (row - MP)) * D + col) = ga;
;                         } else *(f32x4*)(X + (size_t)row * D + col) = *(const f32x4*)(base + col) + ga; } }
;     }
.Lepi_dn_split:
	s_mov_b32 s66, 0x18000
	s_mov_b32 s67, 0
	s_mov_b32 s68, 0x78000
	s_mov_b32 s69, 0
	v_add_u32_e32 v207, 0xffffc000, v207
	s_lshr_b32 s2, s6, 8
	s_lshl_b32 s2, s2, 21
	s_add_u32 s2, s41, s2
	s_addc_u32 s3, s42, 0
	v_lshlrev_b32_e32 v159, 2, v159
	v_lshl_add_u32 v196, v207, 12, v159
	v_lshl_add_u64 v[146:147], v[196:197], 0, s[2:3]
	v_lshrrev_b32_e32 v207, 2, v207
	v_add_u32_e32 v207, 4, v207
	v_mad_u32_u24 v196, v207, s80, v159
	v_lshl_add_u64 v[144:145], v[196:197], 0, s[12:13]
	global_load_dwordx4 v[208:211], v[144:145], off
	global_load_dwordx4 v[212:215], v[144:145], off offset:64
	global_load_dwordx4 v[216:219], v[144:145], off offset:512
	global_load_dwordx4 v[220:223], v[144:145], off offset:576
	v_lshl_add_u64 v[144:145], v[144:145], 0, s[66:67]
	global_load_dwordx4 v[224:227], v[144:145], off
	global_load_dwordx4 v[228:231], v[144:145], off offset:64
	global_load_dwordx4 v[232:235], v[144:145], off offset:512
	global_load_dwordx4 v[236:239], v[144:145], off offset:576
	v_lshl_add_u64 v[144:145], v[144:145], 0, s[66:67]
	global_load_dwordx4 v[240:243], v[144:145], off
	global_load_dwordx4 v[244:247], v[144:145], off offset:64
	global_load_dwordx4 v[248:251], v[144:145], off offset:512
	global_load_dwordx4 v[184:187], v[144:145], off offset:576
	v_lshl_add_u64 v[144:145], v[144:145], 0, s[66:67]
	s_waitcnt vmcnt(8)
	v_pk_mul_f32 v[126:127], v[126:127], v[210:211]
	v_pk_mul_f32 v[124:125], v[124:125], v[208:209]
	v_pk_mul_f32 v[122:123], v[122:123], v[214:215]
	v_pk_mul_f32 v[120:121], v[120:121], v[212:213]
	v_pk_mul_f32 v[118:119], v[118:119], v[218:219]
	v_pk_mul_f32 v[116:117], v[116:117], v[216:217]
	v_pk_mul_f32 v[114:115], v[114:115], v[222:223]
	v_pk_mul_f32 v[112:113], v[112:113], v[220:221]
	global_store_dwordx4 v[146:147], v[124:127], off
	global_store_dwordx4 v[146:147], v[120:123], off offset:64
	global_store_dwordx4 v[146:147], v[116:119], off offset:512
	global_store_dwordx4 v[146:147], v[112:115], off offset:576
	v_lshl_add_u64 v[146:147], v[146:147], 0, s[70:71]
	global_load_dwordx4 v[208:211], v[144:145], off
	global_load_dwordx4 v[212:215], v[144:145], off offset:64
	global_load_dwordx4 v[216:219], v[144:145], off offset:512
	global_load_dwordx4 v[220:223], v[144:145], off offset:576
	v_lshl_add_u64 v[144:145], v[144:145], 0, s[68:69]
	s_waitcnt vmcnt(12)
	v_pk_mul_f32 v[110:111], v[110:111], v[226:227]
	v_pk_mul_f32 v[108:109], v[108:109], v[224:225]
	v_pk_mul_f32 v[106:107], v[106:107], v[230:231]
	v_pk_mul_f32 v[104:105], v[104:105], v[228:229]
	v_pk_mul_f32 v[102:103], v[102:103], v[234:235]
	v_pk_mul_f32 v[100:101], v[100:101], v[232:233]
	v_pk_mul_f32 v[98:99], v[98:99], v[238:239]
	v_pk_mul_f32 v[96:97], v[96:97], v[236:237]
	global_store_dwordx4 v[146:147], v[108:111], off
	global_store_dwordx4 v[146:147], v[104:107], off offset:64
	global_store_dwordx4 v[146:147], v[100:103], off offset:512
	global_store_dwordx4 v[146:147], v[96:99], off offset:576
	v_lshl_add_u64 v[146:147], v[146:147], 0, s[70:71]
	global_load_dwordx4 v[224:227], v[144:145], off
	global_load_dwordx4 v[228:231], v[144:145], off offset:64
	global_load_dwordx4 v[232:235], v[144:145], off offset:512
	global_load_dwordx4 v[236:239], v[144:145], off offset:576
	v_lshl_add_u64 v[144:145], v[144:145], 0, s[66:67]
	s_waitcnt vmcnt(16)
	v_pk_mul_f32 v[94:95], v[94:95], v[242:243]
	v_pk_mul_f32 v[92:93], v[92:93], v[240:241]
	v_pk_mul_f32 v[90:91], v[90:91], v[246:247]
	v_pk_mul_f32 v[88:89], v[88:89], v[244:245]
	v_pk_mul_f32 v[86:87], v[86:87], v[250:251]
	v_pk_mul_f32 v[84:85], v[84:85], v[248:249]
	v_pk_mul_f32 v[82:83], v[82:83], v[186:187]
	v_pk_mul_f32 v[80:81], v[80:81], v[184:185]
	global_store_dwordx4 v[146:147], v[92:95], off
	global_store_dwordx4 v[146:147], v[88:91], off offset:64
	global_store_dwordx4 v[146:147], v[84:87], off offset:512
	global_store_dwordx4 v[146:147], v[80:83], off offset:576
	v_lshl_add_u64 v[146:147], v[146:147], 0, s[70:71]
	global_load_dwordx4 v[240:243], v[144:145], off
	global_load_dwordx4 v[244:247], v[144:145], off offset:64
	global_load_dwordx4 v[248:251], v[144:145], off offset:512
	global_load_dwordx4 v[184:187], v[144:145], off offset:576
	v_lshl_add_u64 v[144:145], v[144:145], 0, s[66:67]
	s_waitcnt vmcnt(16)
;     __device__ __forceinline__ void operator()(const Acc& acc, const Unit& u, int wr, int wc, int fr, int fq) const {
; #pragma unroll
;         for (int ai = 0; ai < 2; ++ai)
; #pragma unroll
;             for (int m = 0; m < 4; ++m) { const int row = u.pm * 256 + ai * 128 + wr * 64 + m * 16 + fr;
;                 const float* base = xp ? (row < MP ? xp + (size_t)row * D : xs + (size_t)(row - MP) * D) : X + (size_t)row * D;
;                 const float* gp = gate + (size_t)mod_row(row) * 6144;
; #pragma unroll
;                 for (int bj = 0; bj < 2; ++bj)
; #pragma unroll
;                     for (int n = 0; n < 2; ++n) { const int col = u.pn * 256 + bj * 128 + wc * 32 + n * 16 + fq * 4;
;                         const f32x4 ga = *(const f32x4*)(gp + col) * acc[ai][bj][m][n];
;                         if (u.split) { *(f32x4*)(part + ((size_t)(u.k0 >> 8) * MS + (row - MP)) * D + col) = ga;
;                         } else *(f32x4*)(X + (size_t)row * D + col) = *(const f32x4*)(base + col) + ga; } }
;     }
	v_pk_mul_f32 v[78:79], v[78:79], v[210:211]
	v_pk_mul_f32 v[76:77], v[76:77], v[208:209]
	v_pk_mul_f32 v[74:75], v[74:75], v[214:215]
	v_pk_mul_f32 v[72:73], v[72:73], v[212:213]
	v_pk_mul_f32 v[70:71], v[70:71], v[218:219]
	v_pk_mul_f32 v[68:69], v[68:69], v[216:217]
	v_pk_mul_f32 v[66:67], v[66:67], v[222:223]
	v_pk_mul_f32 v[64:65], v[64:65], v[220:221]
	global_store_dwordx4 v[146:147], v[76:79], off
	global_store_dwordx4 v[146:147], v[72:75], off offset:64
	global_store_dwordx4 v[146:147], v[68:71], off offset:512
	global_store_dwordx4 v[146:147], v[64:67], off offset:576
	v_lshl_add_u64 v[146:147], v[146:147], 0, s[98:99]
	global_load_dwordx4 v[208:211], v[144:145], off
	global_load_dwordx4 v[212:215], v[144:145], off offset:64
	global_load_dwordx4 v[216:219], v[144:145], off offset:512
	global_load_dwordx4 v[220:223], v[144:145], off offset:576
	v_lshl_add_u64 v[144:145], v[144:145], 0, s[66:67]
	s_waitcnt vmcnt(16)
	v_pk_mul_f32 v[62:63], v[62:63], v[226:227]
	v_pk_mul_f32 v[60:61], v[60:61], v[224:225]
	v_pk_mul_f32 v[58:59], v[58:59], v[230:231]
	v_pk_mul_f32 v[56:57], v[56:57], v[228:229]
	v_pk_mul_f32 v[54:55], v[54:55], v[234:235]
	v_pk_mul_f32 v[52:53], v[52:53], v[232:233]
	v_pk_mul_f32 v[50:51], v[50:51], v[238:239]
	v_pk_mul_f32 v[48:49], v[48:49], v[236:237]
	global_store_dwordx4 v[146:147], v[60:63], off
	global_store_dwordx4 v[146:147], v[56:59], off offset:64
	global_store_dwordx4 v[146:147], v[52:55], off offset:512
	global_store_dwordx4 v[146:147], v[48:51], off offset:576
	v_lshl_add_u64 v[146:147], v[146:147], 0, s[70:71]
	global_load_dwordx4 v[224:227], v[144:145], off
	global_load_dwordx4 v[228:231], v[144:145], off offset:64
	global_load_dwordx4 v[232:235], v[144:145], off offset:512
	global_load_dwordx4 v[236:239], v[144:145], off offset:576
	s_waitcnt vmcnt(16)
	v_pk_mul_f32 v[46:47], v[46:47], v[242:243]
	v_pk_mul_f32 v[44:45], v[44:45], v[240:241]
	v_pk_mul_f32 v[42:43], v[42:43], v[246:247]
	v_pk_mul_f32 v[40:41], v[40:41], v[244:245]
	v_pk_mul_f32 v[38:39], v[38:39], v[250:251]
	v_pk_mul_f32 v[36:37], v[36:37], v[248:249]
	v_pk_mul_f32 v[34:35], v[34:35], v[186:187]
	v_pk_mul_f32 v[32:33], v[32:33], v[184:185]
	global_store_dwordx4 v[146:147], v[44:47], off
	global_store_dwordx4 v[146:147], v[40:43], off offset:64
	global_store_dwordx4 v[146:147], v[36:39], off offset:512
	global_store_dwordx4 v[146:147], v[32:35], off offset:576
	v_lshl_add_u64 v[146:147], v[146:147], 0, s[70:71]
	s_waitcnt vmcnt(12)
	v_pk_mul_f32 v[30:31], v[30:31], v[210:211]
	v_pk_mul_f32 v[28:29], v[28:29], v[208:209]
	v_pk_mul_f32 v[26:27], v[26:27], v[214:215]
	v_pk_mul_f32 v[24:25], v[24:25], v[212:213]
	v_pk_mul_f32 v[22:23], v[22:23], v[218:219]
	v_pk_mul_f32 v[20:21], v[20:21], v[216:217]
	v_pk_mul_f32 v[18:19], v[18:19], v[222:223]
	v_pk_mul_f32 v[16:17], v[16:17], v[220:221]
	global_store_dwordx4 v[146:147], v[28:31], off
	global_store_dwordx4 v[146:147], v[24:27], off offset:64
	global_store_dwordx4 v[146:147], v[20:23], off offset:512
	global_store_dwordx4 v[146:147], v[16:19], off offset:576
	v_lshl_add_u64 v[146:147], v[146:147], 0, s[70:71]
	s_waitcnt vmcnt(8)
	v_pk_mul_f32 v[14:15], v[14:15], v[226:227]
	v_pk_mul_f32 v[12:13], v[12:13], v[224:225]
	v_pk_mul_f32 v[10:11], v[10:11], v[230:231]
	v_pk_mul_f32 v[8:9], v[8:9], v[228:229]
	v_pk_mul_f32 v[6:7], v[6:7], v[234:235]
	v_pk_mul_f32 v[4:5], v[4:5], v[232:233]
	v_pk_mul_f32 v[2:3], v[2:3], v[238:239]
	v_pk_mul_f32 v[0:1], v[0:1], v[236:237]
	global_store_dwordx4 v[146:147], v[12:15], off
	global_store_dwordx4 v[146:147], v[8:11], off offset:64
	global_store_dwordx4 v[146:147], v[4:7], off offset:512
	global_store_dwordx4 v[146:147], v[0:3], off offset:576
.Lepi_dn_done:
	s_and_b64 vcc, exec, s[0:1]
	s_mov_b64 s[0:1], -1
	s_cbranch_vccnz .LBB0_1864
	s_andn2_b64 vcc, exec, s[8:9]
	s_cbranch_vccnz .LBB0_1863
	s_barrier
	s_branch .LBB0_1863
